# q8 + LRU prologue parameter/gate-weight loads and cross-attention first K/V/Q loads prefetched during the preceding epilogues
# speedup vs baseline: 1.0178x; 1.0020x over previous
.LBB0_208:
	s_waitcnt vmcnt(0)
	v_lshlrev_b32_e32 v2, 1, v111
	v_lshl_add_u64 v[14:15], v[82:83], 0, v[2:3]
	global_load_dwordx2 v[20:21], v[14:15], off offset:3072
	v_readlane_b32 s8, v244, 0
	v_lshlrev_b32_e32 v18, 2, v111
	v_readlane_b32 s12, v244, 4
	v_readlane_b32 s13, v244, 5
	v_mov_b32_e32 v16, v110
	s_nop 1
	v_permlane16_swap_b32 v16, v110
	v_readlane_b32 s4, v244, 57
	v_lshlrev_b64 v[12:13], 11, v[80:81]
	v_readlane_b32 s6, v244, 59
	v_readlane_b32 s7, v244, 60
	global_load_dwordx4 v[8:11], v18, s[12:13] offset:2048
	global_load_dwordx2 v[46:47], v[14:15], off offset:3104
	global_load_dwordx2 v[52:53], v[14:15], off offset:3136
	global_load_dwordx2 v[54:55], v[14:15], off offset:3168
	global_load_dwordx4 v[56:59], v18, s[12:13] offset:2112
	global_load_dwordx4 v[60:63], v18, s[12:13] offset:2176
	global_load_dwordx4 v[64:67], v18, s[12:13] offset:2240
	global_load_dwordx2 v[68:69], v[14:15], off offset:3200
	global_load_dwordx4 v[70:73], v18, s[12:13] offset:2304
	global_load_dwordx2 v[74:75], v[14:15], off offset:3232
	global_load_dwordx2 v[76:77], v[14:15], off offset:3264
	global_load_dwordx2 v[78:79], v[14:15], off offset:3296
	global_load_dwordx4 v[84:87], v18, s[12:13] offset:2368
	global_load_dwordx4 v[88:91], v18, s[12:13] offset:2432
	global_load_dwordx4 v[92:95], v18, s[12:13] offset:2496
	global_load_dwordx2 v[96:97], v[14:15], off offset:3328
	global_load_dwordx4 v[98:101], v18, s[12:13] offset:2560
	global_load_dwordx2 v[102:103], v[14:15], off offset:3360
	global_load_dwordx2 v[104:105], v[14:15], off offset:3392
	global_load_dwordx2 v[106:107], v[14:15], off offset:3424
	global_load_dwordx4 v[116:119], v18, s[12:13] offset:2624
	global_load_dwordx4 v[120:123], v18, s[12:13] offset:2688
	global_load_dwordx4 v[124:127], v18, s[12:13] offset:2752
	global_load_dwordx2 v[132:133], v[14:15], off offset:3456
	global_load_dwordx4 v[134:137], v18, s[12:13] offset:2816
	global_load_dwordx2 v[138:139], v[14:15], off offset:3488
	global_load_dwordx2 v[140:141], v[14:15], off offset:3520
	global_load_dwordx2 v[142:143], v[14:15], off offset:3552
	global_load_dwordx4 v[144:147], v18, s[12:13] offset:2880
	global_load_dwordx4 v[148:151], v18, s[12:13] offset:2944
	global_load_dwordx4 v[152:155], v18, s[12:13] offset:3008
	v_readlane_b32 s24, v243, 8
	v_readlane_b32 s26, v244, 50
	v_readlane_b32 s27, v244, 51
	v_readlane_b32 s28, v243, 30
	v_readlane_b32 s30, v243, 5
	v_readlane_b32 s31, v243, 6
	v_lshrrev_b32_e32 v108, 1, v0
	v_and_b32_e32 v129, 1, v0
	v_and_b32_e32 v168, 15, v0
	v_lshrrev_b32_e32 v169, 6, v0
	v_lshl_add_u32 v108, s24, 8, v108
	v_lshlrev_b32_e32 v129, 6, v129
	v_or_b32_e32 v168, s28, v168
	v_lshl_add_u32 v108, v108, 10, v129
	v_lshl_add_u32 v168, v169, 4, v168
	v_bfe_u32 v169, v0, 4, 2
	v_mul_u32_u24_e32 v168, 0x1200, v168
	v_lshl_add_u32 v168, v169, 4, v168
	global_load_dwordx4 v[156:159], v108, s[26:27] offset:48
	global_load_dwordx4 v[160:163], v108, s[26:27] offset:32
	global_load_dwordx4 v[164:167], v108, s[26:27] offset:16
	global_load_dwordx4 v[172:175], v108, s[26:27]
	global_load_dwordx4 v[176:179], v108, s[26:27] offset:512
	global_load_dwordx4 v[196:199], v108, s[26:27] offset:528
	global_load_dwordx4 v[200:203], v108, s[26:27] offset:544
	global_load_dwordx4 v[204:207], v108, s[26:27] offset:560
	global_load_dwordx4 v[208:211], v168, s[30:31] offset:3584
	global_load_dwordx4 v[212:215], v168, s[30:31] offset:3648
	s_waitcnt lgkmcnt(0)
	v_add_f32_e32 v19, v110, v16
	v_mov_b32_e32 v28, v19
	s_nop 1
	v_permlane32_swap_b32 v28, v19
	s_mov_b64 s[0:1], 0xdde0400
	v_lshl_add_u64 v[12:13], s[6:7], 0, v[12:13]
	v_lshl_add_u64 v[12:13], v[12:13], 0, s[0:1]
	s_mov_b32 s0, 0x800000
	s_waitcnt lgkmcnt(0)
	v_add_f32_e32 v19, v19, v28
	v_fmamk_f32 v19, v19, 0x3b800000, v180
	v_mul_f32_e32 v28, 0x4b800000, v19
	v_cmp_gt_f32_e32 vcc, s0, v19
	ds_read2_b64 v[4:7], v109 offset1:4
	v_cndmask_b32_e32 v19, v19, v28, vcc
	v_rsq_f32_e32 v19, v19
	v_lshl_add_u64 v[26:27], v[12:13], 0, v[2:3]
	s_waitcnt lgkmcnt(0)
	v_lshlrev_b32_e32 v29, 16, v4
	v_and_b32_e32 v31, 0xffff0000, v4
	v_mul_f32_e32 v4, 0x45800000, v19
	v_lshlrev_b32_e32 v33, 16, v5
	v_and_b32_e32 v35, 0xffff0000, v5
	v_cndmask_b32_e32 v5, v19, v4, vcc
	v_mov_b32_e32 v38, v5
	v_mov_b32_e32 v40, v5
	v_mov_b32_e32 v42, v5
	v_readlane_b32 s88, v243, 5
	v_readlane_b32 s20, v243, 30
	v_readlane_b32 s89, v243, 6
	v_readlane_b32 s0, v243, 8
	v_mov_b32_e32 v45, v3
	v_mov_b32_e32 v115, v3
	v_readlane_b32 s2, v244, 62
	v_readlane_b32 s10, v244, 2
	v_readlane_b32 s11, v244, 3
	v_mov_b32_e32 v51, v3
	v_readlane_b32 s9, v244, 1
	v_readlane_b32 s3, v244, 63
	v_readlane_b32 s14, v244, 6
	v_readlane_b32 s15, v244, 7
	v_readlane_b32 s5, v244, 58
	v_readlane_b32 s86, v243, 3
	v_readlane_b32 s22, v243, 28
	v_mov_b32_e32 v130, 0
	s_mov_b64 s[4:5], 0
	v_readlane_b32 s58, v243, 2
	v_readlane_b32 s87, v243, 4
	s_movk_i32 s84, 0x7f
	v_readlane_b32 s23, v243, 29
	v_readlane_b32 s21, v243, 31
	s_waitcnt vmcnt(41)
	v_lshlrev_b32_e32 v28, 16, v20
	v_mul_f32_e32 v4, 0xbfb8aa3b, v28
	v_exp_f32_e32 v4, v4
	v_and_b32_e32 v30, 0xffff0000, v20
	v_mul_f32_e32 v19, 0xbfb8aa3b, v30
	v_exp_f32_e32 v19, v19
	v_add_f32_e32 v4, 1.0, v4
	v_rcp_f32_e32 v4, v4
	v_lshlrev_b32_e32 v32, 16, v21
	v_and_b32_e32 v34, 0xffff0000, v21
	v_mul_f32_e32 v20, 0xbfb8aa3b, v32
	v_mul_f32_e32 v21, 0xbfb8aa3b, v34
	v_exp_f32_e32 v36, v20
	v_add_f32_e32 v19, 1.0, v19
	v_exp_f32_e32 v37, v21
	v_pk_mul_f32 v[20:21], v[4:5], v[28:29]
	v_rcp_f32_e32 v4, v19
	v_add_f32_e32 v19, 1.0, v36
	s_waitcnt vmcnt(40)
	v_mul_f32_e32 v8, v8, v21
	v_add_f32_e32 v36, 1.0, v37
	v_pk_mul_f32 v[28:29], v[4:5], v[30:31]
	v_rcp_f32_e32 v4, v19
	v_mul_f32_e32 v19, v20, v8
	v_mul_f32_e32 v8, v9, v29
	v_mul_f32_e32 v20, v28, v8
	v_pk_mul_f32 v[8:9], v[4:5], v[32:33]
	v_rcp_f32_e32 v4, v36
	v_mul_f32_e32 v9, v10, v9
	v_mul_f32_e32 v10, v8, v9
	v_cvt_pk_bf16_f32 v20, v19, v20
	v_pk_mul_f32 v[8:9], v[4:5], v[34:35]
	v_lshlrev_b32_e32 v28, 16, v7
	v_mul_f32_e32 v4, v11, v9
	v_mul_f32_e32 v4, v8, v4
	v_cvt_pk_bf16_f32 v21, v10, v4
	global_store_dwordx2 v[26:27], v[20:21], off
	v_and_b32_e32 v30, 0xffff0000, v7
	s_waitcnt vmcnt(40)
	v_lshlrev_b32_e32 v27, 16, v46
	v_and_b32_e32 v7, 0xffff0000, v46
	v_lshlrev_b32_e32 v29, 16, v47
	v_and_b32_e32 v31, 0xffff0000, v47
	v_mul_f32_e32 v4, 0xbfb8aa3b, v27
	v_mul_f32_e32 v19, 0xbfb8aa3b, v7
	v_mul_f32_e32 v22, 0xbfb8aa3b, v29
	v_mul_f32_e32 v23, 0xbfb8aa3b, v31
	v_exp_f32_e32 v4, v4
	v_exp_f32_e32 v19, v19
	v_exp_f32_e32 v22, v22
	v_exp_f32_e32 v23, v23
	v_add_f32_e32 v4, 1.0, v4
	v_add_f32_e32 v19, 1.0, v19
	v_add_f32_e32 v22, 1.0, v22
	v_add_f32_e32 v23, 1.0, v23
	v_rcp_f32_e32 v33, v4
	v_rcp_f32_e32 v35, v19
	v_rcp_f32_e32 v37, v22
	v_rcp_f32_e32 v39, v23
	v_lshlrev_b32_e32 v26, 16, v6
	v_and_b32_e32 v6, 0xffff0000, v6
	v_mov_b32_e32 v32, v5
	v_mov_b32_e32 v34, v5
	v_mov_b32_e32 v36, v5
	v_pk_mul_f32 v[22:23], v[32:33], v[26:27]
	v_pk_mul_f32 v[6:7], v[34:35], v[6:7]
	v_pk_mul_f32 v[26:27], v[36:37], v[28:29]
	v_mov_b32_e32 v21, v3
	v_or_b32_e32 v20, 32, v2
	v_pk_mul_f32 v[28:29], v[38:39], v[30:31]
	v_lshl_add_u64 v[20:21], v[12:13], 0, v[20:21]
	s_waitcnt vmcnt(39)
	v_and_b32_e32 v31, 0xffff0000, v53
	s_waitcnt vmcnt(37)
	v_mul_f32_e32 v4, v56, v22
	v_mul_f32_e32 v6, v57, v6
	v_mul_f32_e32 v8, v58, v26
	v_mul_f32_e32 v9, v59, v28
	v_mul_f32_e32 v6, v6, v7
	v_mul_f32_e32 v7, v8, v27
	v_mul_f32_e32 v4, v4, v23
	v_mul_f32_e32 v8, v9, v29
	v_cvt_pk_bf16_f32 v6, v4, v6
	v_cvt_pk_bf16_f32 v7, v7, v8
	global_store_dwordx2 v[20:21], v[6:7], off
	ds_read2_b64 v[20:23], v109 offset0:8 offset1:12
	v_lshlrev_b32_e32 v27, 16, v52
	v_lshlrev_b32_e32 v29, 16, v53
	v_mul_f32_e32 v4, 0xbfb8aa3b, v27
	v_mul_f32_e32 v25, 0xbfb8aa3b, v31
	s_waitcnt lgkmcnt(0)
	v_lshlrev_b32_e32 v28, 16, v21
	v_and_b32_e32 v30, 0xffff0000, v21
	v_and_b32_e32 v21, 0xffff0000, v52
	v_mul_f32_e32 v19, 0xbfb8aa3b, v21
	v_mul_f32_e32 v24, 0xbfb8aa3b, v29
	v_exp_f32_e32 v4, v4
	v_exp_f32_e32 v19, v19
	v_exp_f32_e32 v24, v24
	v_exp_f32_e32 v25, v25
	v_add_f32_e32 v4, 1.0, v4
	v_add_f32_e32 v19, 1.0, v19
	v_add_f32_e32 v24, 1.0, v24
	v_add_f32_e32 v25, 1.0, v25
	v_rcp_f32_e32 v33, v4
	v_rcp_f32_e32 v35, v19
	v_rcp_f32_e32 v37, v24
	v_rcp_f32_e32 v39, v25
	v_lshlrev_b32_e32 v26, 16, v20
	v_and_b32_e32 v20, 0xffff0000, v20
	v_pk_mul_f32 v[24:25], v[32:33], v[26:27]
	v_pk_mul_f32 v[20:21], v[34:35], v[20:21]
	v_pk_mul_f32 v[26:27], v[36:37], v[28:29]
	v_mov_b32_e32 v11, v3
	v_or_b32_e32 v10, 64, v2
	v_pk_mul_f32 v[28:29], v[38:39], v[30:31]
	v_lshl_add_u64 v[10:11], v[12:13], 0, v[10:11]
	v_mov_b32_e32 v30, v5
	s_waitcnt vmcnt(37)
	v_mul_f32_e32 v4, v60, v24
	v_mul_f32_e32 v6, v61, v20
	v_mul_f32_e32 v7, v62, v26
	v_mul_f32_e32 v8, v63, v28
	v_mul_f32_e32 v6, v6, v21
	v_mul_f32_e32 v7, v7, v27
	v_mul_f32_e32 v4, v4, v25
	v_mul_f32_e32 v8, v8, v29
	v_cvt_pk_bf16_f32 v6, v4, v6
	v_cvt_pk_bf16_f32 v7, v7, v8
	global_store_dwordx2 v[10:11], v[6:7], off
	v_lshlrev_b32_e32 v26, 16, v23
	v_and_b32_e32 v28, 0xffff0000, v23
	v_lshlrev_b32_e32 v21, 16, v54
	v_and_b32_e32 v23, 0xffff0000, v54
	v_lshlrev_b32_e32 v27, 16, v55
	v_and_b32_e32 v29, 0xffff0000, v55
	v_mul_f32_e32 v4, 0xbfb8aa3b, v21
	v_mul_f32_e32 v16, 0xbfb8aa3b, v23
	v_mul_f32_e32 v17, 0xbfb8aa3b, v27
	v_mul_f32_e32 v19, 0xbfb8aa3b, v29
	v_exp_f32_e32 v4, v4
	v_exp_f32_e32 v16, v16
	v_exp_f32_e32 v17, v17
	v_exp_f32_e32 v19, v19
	v_add_f32_e32 v4, 1.0, v4
	v_add_f32_e32 v16, 1.0, v16
	v_add_f32_e32 v17, 1.0, v17
	v_add_f32_e32 v19, 1.0, v19
	v_rcp_f32_e32 v31, v4
	v_rcp_f32_e32 v33, v16
	v_rcp_f32_e32 v35, v17
	v_rcp_f32_e32 v37, v19
	v_lshlrev_b32_e32 v20, 16, v22
	v_and_b32_e32 v22, 0xffff0000, v22
	v_pk_mul_f32 v[16:17], v[30:31], v[20:21]
	v_pk_mul_f32 v[20:21], v[32:33], v[22:23]
	v_pk_mul_f32 v[22:23], v[34:35], v[26:27]
	v_mov_b32_e32 v11, v3
	v_or_b32_e32 v10, 0x60, v2
	v_pk_mul_f32 v[26:27], v[36:37], v[28:29]
	v_lshl_add_u64 v[10:11], v[12:13], 0, v[10:11]
	s_waitcnt vmcnt(37)
	v_mul_f32_e32 v4, v64, v16
	v_mul_f32_e32 v6, v65, v20
	v_mul_f32_e32 v7, v66, v22
	v_mul_f32_e32 v8, v67, v26
	v_mul_f32_e32 v6, v6, v21
	v_mul_f32_e32 v7, v7, v23
	v_mul_f32_e32 v4, v4, v17
	v_mul_f32_e32 v8, v8, v27
	v_cvt_pk_bf16_f32 v6, v4, v6
	v_cvt_pk_bf16_f32 v7, v7, v8
	global_store_dwordx2 v[10:11], v[6:7], off
	ds_read2_b64 v[20:23], v109 offset0:16 offset1:20
	s_waitcnt vmcnt(37)
	v_lshlrev_b32_e32 v31, 16, v68
	v_lshlrev_b32_e32 v33, 16, v69
	v_and_b32_e32 v35, 0xffff0000, v69
	s_waitcnt lgkmcnt(0)
	v_lshlrev_b32_e32 v32, 16, v21
	v_and_b32_e32 v34, 0xffff0000, v21
	v_and_b32_e32 v21, 0xffff0000, v68
	v_mul_f32_e32 v4, 0xbfb8aa3b, v31
	v_mul_f32_e32 v19, 0xbfb8aa3b, v21
	v_mul_f32_e32 v24, 0xbfb8aa3b, v33
	v_mul_f32_e32 v25, 0xbfb8aa3b, v35
	v_exp_f32_e32 v4, v4
	v_exp_f32_e32 v19, v19
	v_exp_f32_e32 v24, v24
	v_exp_f32_e32 v25, v25
	v_add_f32_e32 v4, 1.0, v4
	v_add_f32_e32 v19, 1.0, v19
	v_add_f32_e32 v24, 1.0, v24
	v_add_f32_e32 v25, 1.0, v25
	v_rcp_f32_e32 v37, v4
	v_rcp_f32_e32 v39, v19
	v_rcp_f32_e32 v41, v24
	v_rcp_f32_e32 v43, v25
	v_lshlrev_b32_e32 v30, 16, v20
	v_and_b32_e32 v20, 0xffff0000, v20
	v_pk_mul_f32 v[24:25], v[36:37], v[30:31]
	v_pk_mul_f32 v[20:21], v[38:39], v[20:21]
	v_pk_mul_f32 v[30:31], v[40:41], v[32:33]
	v_mov_b32_e32 v17, v3
	v_or_b32_e32 v16, 0x80, v2
	v_pk_mul_f32 v[32:33], v[42:43], v[34:35]
	v_lshl_add_u64 v[16:17], v[12:13], 0, v[16:17]
	v_mov_b32_e32 v34, v5
	s_waitcnt vmcnt(36)
	v_mul_f32_e32 v4, v70, v24
	v_mul_f32_e32 v8, v71, v20
	v_mul_f32_e32 v9, v72, v30
	v_mul_f32_e32 v10, v73, v32
	v_mul_f32_e32 v8, v8, v21
	v_mul_f32_e32 v9, v9, v31
	v_mul_f32_e32 v4, v4, v25
	v_mul_f32_e32 v10, v10, v33
	v_cvt_pk_bf16_f32 v8, v4, v8
	v_cvt_pk_bf16_f32 v9, v9, v10
	global_store_dwordx2 v[16:17], v[8:9], off
	v_lshlrev_b32_e32 v24, 16, v23
	v_and_b32_e32 v30, 0xffff0000, v23
	s_waitcnt vmcnt(36)
	v_lshlrev_b32_e32 v21, 16, v74
	v_and_b32_e32 v23, 0xffff0000, v74
	v_lshlrev_b32_e32 v25, 16, v75
	v_and_b32_e32 v31, 0xffff0000, v75
	v_mul_f32_e32 v4, 0xbfb8aa3b, v21
	v_mul_f32_e32 v19, 0xbfb8aa3b, v23
	v_mul_f32_e32 v26, 0xbfb8aa3b, v25
	v_mul_f32_e32 v27, 0xbfb8aa3b, v31
	v_exp_f32_e32 v4, v4
	v_exp_f32_e32 v19, v19
	v_exp_f32_e32 v26, v26
	v_exp_f32_e32 v27, v27
	v_add_f32_e32 v4, 1.0, v4
	v_add_f32_e32 v19, 1.0, v19
	v_add_f32_e32 v26, 1.0, v26
	v_add_f32_e32 v27, 1.0, v27
	v_rcp_f32_e32 v33, v4
	v_rcp_f32_e32 v35, v19
	v_rcp_f32_e32 v37, v26
	v_rcp_f32_e32 v39, v27
	v_lshlrev_b32_e32 v20, 16, v22
	v_and_b32_e32 v22, 0xffff0000, v22
	v_mov_b32_e32 v32, v5
	v_pk_mul_f32 v[20:21], v[32:33], v[20:21]
	v_pk_mul_f32 v[22:23], v[34:35], v[22:23]
	v_pk_mul_f32 v[24:25], v[36:37], v[24:25]
	v_mov_b32_e32 v17, v3
	v_or_b32_e32 v16, 0xa0, v2
	v_pk_mul_f32 v[26:27], v[38:39], v[30:31]
	v_lshl_add_u64 v[16:17], v[12:13], 0, v[16:17]
	s_waitcnt vmcnt(35)
	v_and_b32_e32 v31, 0xffff0000, v77
	s_waitcnt vmcnt(33)
	v_mul_f32_e32 v4, v84, v20
	v_mul_f32_e32 v8, v85, v22
	v_mul_f32_e32 v9, v86, v24
	v_mul_f32_e32 v10, v87, v26
	v_mul_f32_e32 v8, v8, v23
	v_mul_f32_e32 v9, v9, v25
	v_mul_f32_e32 v4, v4, v21
	v_mul_f32_e32 v10, v10, v27
	v_cvt_pk_bf16_f32 v8, v4, v8
	v_cvt_pk_bf16_f32 v9, v9, v10
	global_store_dwordx2 v[16:17], v[8:9], off
	ds_read2_b64 v[20:23], v109 offset0:24 offset1:28
	v_lshlrev_b32_e32 v25, 16, v76
	v_lshlrev_b32_e32 v27, 16, v77
	v_mul_f32_e32 v4, 0xbfb8aa3b, v25
	v_mul_f32_e32 v29, 0xbfb8aa3b, v31
	s_waitcnt lgkmcnt(0)
	v_lshlrev_b32_e32 v26, 16, v21
	v_and_b32_e32 v30, 0xffff0000, v21
	v_and_b32_e32 v21, 0xffff0000, v76
	v_mul_f32_e32 v19, 0xbfb8aa3b, v21
	v_mul_f32_e32 v28, 0xbfb8aa3b, v27
	v_exp_f32_e32 v4, v4
	v_exp_f32_e32 v19, v19
	v_exp_f32_e32 v28, v28
	v_exp_f32_e32 v29, v29
	v_add_f32_e32 v4, 1.0, v4
	v_add_f32_e32 v19, 1.0, v19
	v_add_f32_e32 v28, 1.0, v28
	v_add_f32_e32 v29, 1.0, v29
	v_rcp_f32_e32 v33, v4
	v_rcp_f32_e32 v35, v19
	v_rcp_f32_e32 v37, v28
	v_rcp_f32_e32 v39, v29
	v_lshlrev_b32_e32 v24, 16, v20
	v_and_b32_e32 v20, 0xffff0000, v20
	v_pk_mul_f32 v[24:25], v[32:33], v[24:25]
	v_pk_mul_f32 v[20:21], v[34:35], v[20:21]
	v_pk_mul_f32 v[26:27], v[36:37], v[26:27]
	v_mov_b32_e32 v17, v3
	v_or_b32_e32 v16, 0xc0, v2
	v_pk_mul_f32 v[28:29], v[38:39], v[30:31]
	v_lshl_add_u64 v[16:17], v[12:13], 0, v[16:17]
	v_mov_b32_e32 v30, v5
	s_waitcnt vmcnt(33)
	v_mul_f32_e32 v4, v88, v24
	v_mul_f32_e32 v8, v89, v20
	v_mul_f32_e32 v9, v90, v26
	v_mul_f32_e32 v10, v91, v28
	v_mul_f32_e32 v8, v8, v21
	v_mul_f32_e32 v9, v9, v27
	v_mul_f32_e32 v4, v4, v25
	v_mul_f32_e32 v10, v10, v29
	v_cvt_pk_bf16_f32 v8, v4, v8
	v_cvt_pk_bf16_f32 v9, v9, v10
	global_store_dwordx2 v[16:17], v[8:9], off
	v_lshlrev_b32_e32 v26, 16, v23
	v_and_b32_e32 v28, 0xffff0000, v23
	v_lshlrev_b32_e32 v21, 16, v78
	v_and_b32_e32 v23, 0xffff0000, v78
	v_lshlrev_b32_e32 v27, 16, v79
	v_and_b32_e32 v29, 0xffff0000, v79
	v_mul_f32_e32 v4, 0xbfb8aa3b, v21
	v_mul_f32_e32 v6, 0xbfb8aa3b, v23
	v_mul_f32_e32 v7, 0xbfb8aa3b, v27
	v_mul_f32_e32 v19, 0xbfb8aa3b, v29
	v_exp_f32_e32 v4, v4
	v_exp_f32_e32 v6, v6
	v_exp_f32_e32 v7, v7
	v_exp_f32_e32 v19, v19
	v_add_f32_e32 v4, 1.0, v4
	v_add_f32_e32 v6, 1.0, v6
	v_add_f32_e32 v7, 1.0, v7
	v_add_f32_e32 v19, 1.0, v19
	v_rcp_f32_e32 v31, v4
	v_rcp_f32_e32 v33, v6
	v_rcp_f32_e32 v35, v7
	v_rcp_f32_e32 v37, v19
	v_lshlrev_b32_e32 v20, 16, v22
	v_and_b32_e32 v22, 0xffff0000, v22
	v_pk_mul_f32 v[6:7], v[30:31], v[20:21]
	v_pk_mul_f32 v[20:21], v[32:33], v[22:23]
	v_pk_mul_f32 v[22:23], v[34:35], v[26:27]
	v_mov_b32_e32 v17, v3
	v_or_b32_e32 v16, 0xe0, v2
	v_pk_mul_f32 v[26:27], v[36:37], v[28:29]
	v_lshl_add_u64 v[16:17], v[12:13], 0, v[16:17]
	s_waitcnt vmcnt(33)
	v_mul_f32_e32 v4, v92, v6
	v_mul_f32_e32 v6, v93, v20
	v_mul_f32_e32 v8, v94, v22
	v_mul_f32_e32 v9, v95, v26
	v_mul_f32_e32 v4, v4, v7
	v_mul_f32_e32 v6, v6, v21
	v_mul_f32_e32 v7, v8, v23
	v_mul_f32_e32 v8, v9, v27
	v_cvt_pk_bf16_f32 v6, v4, v6
	v_cvt_pk_bf16_f32 v7, v7, v8
	global_store_dwordx2 v[16:17], v[6:7], off
	ds_read2_b64 v[20:23], v109 offset0:32 offset1:36
	s_waitcnt vmcnt(33)
	v_lshlrev_b32_e32 v31, 16, v96
	v_lshlrev_b32_e32 v33, 16, v97
	v_and_b32_e32 v35, 0xffff0000, v97
	s_waitcnt lgkmcnt(0)
	v_lshlrev_b32_e32 v32, 16, v21
	v_and_b32_e32 v34, 0xffff0000, v21
	v_and_b32_e32 v21, 0xffff0000, v96
	v_mul_f32_e32 v4, 0xbfb8aa3b, v31
	v_mul_f32_e32 v19, 0xbfb8aa3b, v21
	v_mul_f32_e32 v24, 0xbfb8aa3b, v33
	v_mul_f32_e32 v25, 0xbfb8aa3b, v35
	v_exp_f32_e32 v4, v4
	v_exp_f32_e32 v19, v19
	v_exp_f32_e32 v24, v24
	v_exp_f32_e32 v25, v25
	v_add_f32_e32 v4, 1.0, v4
	v_add_f32_e32 v19, 1.0, v19
	v_add_f32_e32 v24, 1.0, v24
	v_add_f32_e32 v25, 1.0, v25
	v_rcp_f32_e32 v37, v4
	v_rcp_f32_e32 v39, v19
	v_rcp_f32_e32 v41, v24
	v_rcp_f32_e32 v43, v25
	v_lshlrev_b32_e32 v30, 16, v20
	v_and_b32_e32 v20, 0xffff0000, v20
	v_pk_mul_f32 v[24:25], v[36:37], v[30:31]
	v_pk_mul_f32 v[20:21], v[38:39], v[20:21]
	v_pk_mul_f32 v[30:31], v[40:41], v[32:33]
	v_mov_b32_e32 v17, v3
	v_or_b32_e32 v16, 0x100, v2
	v_pk_mul_f32 v[32:33], v[42:43], v[34:35]
	v_lshl_add_u64 v[16:17], v[12:13], 0, v[16:17]
	v_mov_b32_e32 v34, v5
	s_waitcnt vmcnt(32)
	v_mul_f32_e32 v4, v98, v24
	v_mul_f32_e32 v8, v99, v20
	v_mul_f32_e32 v9, v100, v30
	v_mul_f32_e32 v10, v101, v32
	v_mul_f32_e32 v8, v8, v21
	v_mul_f32_e32 v9, v9, v31
	v_mul_f32_e32 v4, v4, v25
	v_mul_f32_e32 v10, v10, v33
	v_cvt_pk_bf16_f32 v8, v4, v8
	v_cvt_pk_bf16_f32 v9, v9, v10
	global_store_dwordx2 v[16:17], v[8:9], off
	v_lshlrev_b32_e32 v24, 16, v23
	v_and_b32_e32 v30, 0xffff0000, v23
	s_waitcnt vmcnt(32)
	v_lshlrev_b32_e32 v21, 16, v102
	v_and_b32_e32 v23, 0xffff0000, v102
	v_lshlrev_b32_e32 v25, 16, v103
	v_and_b32_e32 v31, 0xffff0000, v103
	v_mul_f32_e32 v4, 0xbfb8aa3b, v21
	v_mul_f32_e32 v19, 0xbfb8aa3b, v23
	v_mul_f32_e32 v26, 0xbfb8aa3b, v25
	v_mul_f32_e32 v27, 0xbfb8aa3b, v31
	v_exp_f32_e32 v4, v4
	v_exp_f32_e32 v19, v19
	v_exp_f32_e32 v26, v26
	v_exp_f32_e32 v27, v27
	v_add_f32_e32 v4, 1.0, v4
	v_add_f32_e32 v19, 1.0, v19
	v_add_f32_e32 v26, 1.0, v26
	v_add_f32_e32 v27, 1.0, v27
	v_rcp_f32_e32 v33, v4
	v_rcp_f32_e32 v35, v19
	v_rcp_f32_e32 v37, v26
	v_rcp_f32_e32 v39, v27
	v_lshlrev_b32_e32 v20, 16, v22
	v_and_b32_e32 v22, 0xffff0000, v22
	v_mov_b32_e32 v32, v5
	v_pk_mul_f32 v[20:21], v[32:33], v[20:21]
	v_pk_mul_f32 v[22:23], v[34:35], v[22:23]
	v_pk_mul_f32 v[24:25], v[36:37], v[24:25]
	v_mov_b32_e32 v17, v3
	v_or_b32_e32 v16, 0x120, v2
	v_pk_mul_f32 v[26:27], v[38:39], v[30:31]
	v_lshl_add_u64 v[16:17], v[12:13], 0, v[16:17]
	s_waitcnt vmcnt(31)
	v_and_b32_e32 v31, 0xffff0000, v105
	s_waitcnt vmcnt(29)
	v_mul_f32_e32 v4, v116, v20
	v_mul_f32_e32 v8, v117, v22
	v_mul_f32_e32 v9, v118, v24
	v_mul_f32_e32 v10, v119, v26
	v_mul_f32_e32 v8, v8, v23
	v_mul_f32_e32 v9, v9, v25
	v_mul_f32_e32 v4, v4, v21
	v_mul_f32_e32 v10, v10, v27
	v_cvt_pk_bf16_f32 v8, v4, v8
	v_cvt_pk_bf16_f32 v9, v9, v10
	global_store_dwordx2 v[16:17], v[8:9], off
	ds_read2_b64 v[20:23], v109 offset0:40 offset1:44
	v_lshlrev_b32_e32 v25, 16, v104
	v_lshlrev_b32_e32 v27, 16, v105
	v_mul_f32_e32 v4, 0xbfb8aa3b, v25
	v_mul_f32_e32 v29, 0xbfb8aa3b, v31
	s_waitcnt lgkmcnt(0)
	v_lshlrev_b32_e32 v26, 16, v21
	v_and_b32_e32 v30, 0xffff0000, v21
	v_and_b32_e32 v21, 0xffff0000, v104
	v_mul_f32_e32 v19, 0xbfb8aa3b, v21
	v_mul_f32_e32 v28, 0xbfb8aa3b, v27
	v_exp_f32_e32 v4, v4
	v_exp_f32_e32 v19, v19
	v_exp_f32_e32 v28, v28
	v_exp_f32_e32 v29, v29
	v_add_f32_e32 v4, 1.0, v4
	v_add_f32_e32 v19, 1.0, v19
	v_add_f32_e32 v28, 1.0, v28
	v_add_f32_e32 v29, 1.0, v29
	v_rcp_f32_e32 v33, v4
	v_rcp_f32_e32 v35, v19
	v_rcp_f32_e32 v37, v28
	v_rcp_f32_e32 v39, v29
	v_lshlrev_b32_e32 v24, 16, v20
	v_and_b32_e32 v20, 0xffff0000, v20
	v_pk_mul_f32 v[24:25], v[32:33], v[24:25]
	v_pk_mul_f32 v[20:21], v[34:35], v[20:21]
	v_pk_mul_f32 v[26:27], v[36:37], v[26:27]
	v_mov_b32_e32 v17, v3
	v_or_b32_e32 v16, 0x140, v2
	v_pk_mul_f32 v[28:29], v[38:39], v[30:31]
	v_lshl_add_u64 v[16:17], v[12:13], 0, v[16:17]
	v_mov_b32_e32 v30, v5
	s_waitcnt vmcnt(29)
	v_mul_f32_e32 v4, v120, v24
	v_mul_f32_e32 v8, v121, v20
	v_mul_f32_e32 v9, v122, v26
	v_mul_f32_e32 v10, v123, v28
	v_mul_f32_e32 v8, v8, v21
	v_mul_f32_e32 v9, v9, v27
	v_mul_f32_e32 v4, v4, v25
	v_mul_f32_e32 v10, v10, v29
	v_cvt_pk_bf16_f32 v8, v4, v8
	v_cvt_pk_bf16_f32 v9, v9, v10
	global_store_dwordx2 v[16:17], v[8:9], off
	v_lshlrev_b32_e32 v26, 16, v23
	v_and_b32_e32 v28, 0xffff0000, v23
	v_lshlrev_b32_e32 v21, 16, v106
	v_and_b32_e32 v23, 0xffff0000, v106
	v_lshlrev_b32_e32 v27, 16, v107
	v_and_b32_e32 v29, 0xffff0000, v107
	v_mul_f32_e32 v4, 0xbfb8aa3b, v21
	v_mul_f32_e32 v6, 0xbfb8aa3b, v23
	v_mul_f32_e32 v7, 0xbfb8aa3b, v27
	v_mul_f32_e32 v19, 0xbfb8aa3b, v29
	v_exp_f32_e32 v4, v4
	v_exp_f32_e32 v6, v6
	v_exp_f32_e32 v7, v7
	v_exp_f32_e32 v19, v19
	v_add_f32_e32 v4, 1.0, v4
	v_add_f32_e32 v6, 1.0, v6
	v_add_f32_e32 v7, 1.0, v7
	v_add_f32_e32 v19, 1.0, v19
	v_rcp_f32_e32 v31, v4
	v_rcp_f32_e32 v33, v6
	v_rcp_f32_e32 v35, v7
	v_rcp_f32_e32 v37, v19
	v_lshlrev_b32_e32 v20, 16, v22
	v_and_b32_e32 v22, 0xffff0000, v22
	v_pk_mul_f32 v[6:7], v[30:31], v[20:21]
	v_pk_mul_f32 v[20:21], v[32:33], v[22:23]
	v_pk_mul_f32 v[22:23], v[34:35], v[26:27]
	v_mov_b32_e32 v17, v3
	v_or_b32_e32 v16, 0x160, v2
	v_pk_mul_f32 v[26:27], v[36:37], v[28:29]
	v_lshl_add_u64 v[16:17], v[12:13], 0, v[16:17]
	s_waitcnt vmcnt(29)
	v_mul_f32_e32 v4, v124, v6
	v_mul_f32_e32 v6, v125, v20
	v_mul_f32_e32 v8, v126, v22
	v_mul_f32_e32 v9, v127, v26
	v_mul_f32_e32 v4, v4, v7
	v_mul_f32_e32 v6, v6, v21
	v_mul_f32_e32 v7, v8, v23
	v_mul_f32_e32 v8, v9, v27
	v_cvt_pk_bf16_f32 v6, v4, v6
	v_cvt_pk_bf16_f32 v7, v7, v8
	global_store_dwordx2 v[16:17], v[6:7], off
	ds_read2_b64 v[20:23], v109 offset0:48 offset1:52
	v_mov_b32_e32 v17, v3
	v_or_b32_e32 v16, 0x180, v2
	v_lshl_add_u64 v[14:15], v[12:13], 0, v[16:17]
	s_waitcnt lgkmcnt(0)
	v_lshlrev_b32_e32 v30, 16, v21
	v_and_b32_e32 v32, 0xffff0000, v21
	s_waitcnt vmcnt(29)
	v_lshlrev_b32_e32 v17, 16, v132
	v_and_b32_e32 v21, 0xffff0000, v132
	v_lshlrev_b32_e32 v31, 16, v133
	v_and_b32_e32 v33, 0xffff0000, v133
	v_mul_f32_e32 v4, 0xbfb8aa3b, v17
	v_mul_f32_e32 v19, 0xbfb8aa3b, v21
	v_mul_f32_e32 v24, 0xbfb8aa3b, v31
	v_mul_f32_e32 v25, 0xbfb8aa3b, v33
	v_exp_f32_e32 v4, v4
	v_exp_f32_e32 v19, v19
	v_exp_f32_e32 v24, v24
	v_exp_f32_e32 v25, v25
	v_add_f32_e32 v4, 1.0, v4
	v_add_f32_e32 v19, 1.0, v19
	v_add_f32_e32 v24, 1.0, v24
	v_add_f32_e32 v25, 1.0, v25
	v_rcp_f32_e32 v35, v4
	v_rcp_f32_e32 v37, v19
	v_rcp_f32_e32 v39, v24
	v_rcp_f32_e32 v41, v25
	v_lshlrev_b32_e32 v16, 16, v20
	v_and_b32_e32 v20, 0xffff0000, v20
	v_pk_mul_f32 v[16:17], v[34:35], v[16:17]
	v_pk_mul_f32 v[20:21], v[36:37], v[20:21]
	v_pk_mul_f32 v[24:25], v[38:39], v[30:31]
	v_pk_mul_f32 v[30:31], v[40:41], v[32:33]
	v_mov_b32_e32 v32, v5
	s_waitcnt vmcnt(28)
	v_mul_f32_e32 v4, v134, v16
	v_mul_f32_e32 v8, v135, v20
	v_mul_f32_e32 v9, v136, v24
	v_mul_f32_e32 v10, v137, v30
	v_mul_f32_e32 v8, v8, v21
	v_mul_f32_e32 v9, v9, v25
	v_mul_f32_e32 v4, v4, v17
	v_mul_f32_e32 v10, v10, v31
	v_cvt_pk_bf16_f32 v8, v4, v8
	v_cvt_pk_bf16_f32 v9, v9, v10
	global_store_dwordx2 v[14:15], v[8:9], off
	v_lshlrev_b32_e32 v16, 16, v22
	v_and_b32_e32 v20, 0xffff0000, v22
	v_lshlrev_b32_e32 v22, 16, v23
	v_and_b32_e32 v24, 0xffff0000, v23
	s_waitcnt vmcnt(28)
	v_lshlrev_b32_e32 v17, 16, v138
	v_and_b32_e32 v21, 0xffff0000, v138
	v_lshlrev_b32_e32 v23, 16, v139
	v_and_b32_e32 v25, 0xffff0000, v139
	v_mul_f32_e32 v4, 0xbfb8aa3b, v17
	v_mul_f32_e32 v19, 0xbfb8aa3b, v21
	v_mul_f32_e32 v26, 0xbfb8aa3b, v23
	v_mul_f32_e32 v27, 0xbfb8aa3b, v25
	v_exp_f32_e32 v4, v4
	v_exp_f32_e32 v19, v19
	v_exp_f32_e32 v26, v26
	v_exp_f32_e32 v27, v27
	v_add_f32_e32 v4, 1.0, v4
	v_add_f32_e32 v19, 1.0, v19
	v_add_f32_e32 v26, 1.0, v26
	v_add_f32_e32 v27, 1.0, v27
	v_rcp_f32_e32 v31, v4
	v_rcp_f32_e32 v33, v19
	v_rcp_f32_e32 v35, v26
	v_rcp_f32_e32 v37, v27
	v_mov_b32_e32 v30, v5
	v_pk_mul_f32 v[16:17], v[30:31], v[16:17]
	v_pk_mul_f32 v[20:21], v[32:33], v[20:21]
	v_pk_mul_f32 v[22:23], v[34:35], v[22:23]
	v_mov_b32_e32 v15, v3
	v_or_b32_e32 v14, 0x1a0, v2
	v_pk_mul_f32 v[24:25], v[36:37], v[24:25]
	v_lshl_add_u64 v[14:15], v[12:13], 0, v[14:15]
	s_waitcnt vmcnt(27)
	v_and_b32_e32 v27, 0xffff0000, v141
	s_waitcnt vmcnt(25)
	v_mul_f32_e32 v4, v144, v16
	v_mul_f32_e32 v8, v145, v20
	v_mul_f32_e32 v9, v146, v22
	v_mul_f32_e32 v10, v147, v24
	v_mul_f32_e32 v8, v8, v21
	v_mul_f32_e32 v9, v9, v23
	v_mul_f32_e32 v4, v4, v17
	v_mul_f32_e32 v10, v10, v25
	v_cvt_pk_bf16_f32 v8, v4, v8
	v_cvt_pk_bf16_f32 v9, v9, v10
	global_store_dwordx2 v[14:15], v[8:9], off
	ds_read2_b64 v[14:17], v109 offset0:56 offset1:60
	v_lshlrev_b32_e32 v23, 16, v140
	v_lshlrev_b32_e32 v25, 16, v141
	v_mul_f32_e32 v4, 0xbfb8aa3b, v23
	v_mul_f32_e32 v29, 0xbfb8aa3b, v27
	s_waitcnt lgkmcnt(0)
	v_lshlrev_b32_e32 v24, 16, v15
	v_and_b32_e32 v26, 0xffff0000, v15
	v_and_b32_e32 v15, 0xffff0000, v140
	v_mul_f32_e32 v19, 0xbfb8aa3b, v15
	v_mul_f32_e32 v28, 0xbfb8aa3b, v25
	v_exp_f32_e32 v4, v4
	v_exp_f32_e32 v19, v19
	v_exp_f32_e32 v28, v28
	v_exp_f32_e32 v29, v29
	v_add_f32_e32 v4, 1.0, v4
	v_add_f32_e32 v19, 1.0, v19
	v_add_f32_e32 v28, 1.0, v28
	v_add_f32_e32 v29, 1.0, v29
	v_rcp_f32_e32 v31, v4
	v_rcp_f32_e32 v33, v19
	v_rcp_f32_e32 v35, v28
	v_rcp_f32_e32 v37, v29
	v_lshlrev_b32_e32 v22, 16, v14
	v_and_b32_e32 v14, 0xffff0000, v14
	v_pk_mul_f32 v[22:23], v[30:31], v[22:23]
	v_pk_mul_f32 v[14:15], v[32:33], v[14:15]
	v_pk_mul_f32 v[24:25], v[34:35], v[24:25]
	v_mov_b32_e32 v21, v3
	v_or_b32_e32 v20, 0x1c0, v2
	v_pk_mul_f32 v[26:27], v[36:37], v[26:27]
	v_lshl_add_u64 v[20:21], v[12:13], 0, v[20:21]
	v_or_b32_e32 v2, 0x1e0, v2
	v_mov_b32_e32 v28, v5
	v_lshlrev_b32_e32 v19, 16, v143
	v_lshl_add_u64 v[12:13], v[12:13], 0, v[2:3]
	v_mov_b32_e32 v30, v0
	s_waitcnt vmcnt(25)
	v_mul_f32_e32 v4, v148, v22
	v_mul_f32_e32 v8, v149, v14
	v_mul_f32_e32 v9, v150, v24
	v_mul_f32_e32 v10, v151, v26
	v_mul_f32_e32 v8, v8, v15
	v_mul_f32_e32 v9, v9, v25
	v_mul_f32_e32 v4, v4, v23
	v_mul_f32_e32 v10, v10, v27
	v_cvt_pk_bf16_f32 v8, v4, v8
	v_cvt_pk_bf16_f32 v9, v9, v10
	global_store_dwordx2 v[20:21], v[8:9], off
	v_lshlrev_b32_e32 v18, 16, v17
	v_and_b32_e32 v20, 0xffff0000, v17
	v_mov_b32_e32 v22, v5
	v_mov_b32_e32 v24, v5
	v_mov_b32_e32 v26, v5
	v_lshlrev_b32_e32 v5, 16, v142
	v_and_b32_e32 v17, 0xffff0000, v142
	v_and_b32_e32 v21, 0xffff0000, v143
	v_mul_f32_e32 v2, 0xbfb8aa3b, v5
	v_mul_f32_e32 v6, 0xbfb8aa3b, v17
	v_mul_f32_e32 v7, 0xbfb8aa3b, v19
	v_mul_f32_e32 v23, 0xbfb8aa3b, v21
	v_exp_f32_e32 v2, v2
	v_exp_f32_e32 v6, v6
	v_exp_f32_e32 v7, v7
	v_exp_f32_e32 v23, v23
	v_add_f32_e32 v2, 1.0, v2
	v_add_f32_e32 v6, 1.0, v6
	v_add_f32_e32 v7, 1.0, v7
	v_add_f32_e32 v29, 1.0, v23
	v_rcp_f32_e32 v23, v2
	v_rcp_f32_e32 v25, v6
	v_rcp_f32_e32 v27, v7
	v_rcp_f32_e32 v29, v29
	v_lshlrev_b32_e32 v4, 16, v16
	v_and_b32_e32 v16, 0xffff0000, v16
	v_pk_mul_f32 v[4:5], v[22:23], v[4:5]
	v_pk_mul_f32 v[6:7], v[24:25], v[16:17]
	v_pk_mul_f32 v[16:17], v[26:27], v[18:19]
	v_pk_mul_f32 v[18:19], v[28:29], v[20:21]
	v_mov_b64_e32 v[14:15], s[88:89]
	s_waitcnt vmcnt(25)
	v_mul_f32_e32 v2, v152, v4
	v_mul_f32_e32 v4, v153, v6
	v_mul_f32_e32 v6, v154, v16
	v_mul_f32_e32 v8, v155, v18
	v_mul_f32_e32 v2, v2, v5
	v_mul_f32_e32 v4, v4, v7
	v_mul_f32_e32 v5, v6, v17
	v_mul_f32_e32 v6, v8, v19
	v_cvt_pk_bf16_f32 v4, v2, v4
	v_cvt_pk_bf16_f32 v5, v5, v6
	global_store_dwordx2 v[12:13], v[4:5], off
	s_nop 0
	v_and_b32_e32 v52, 15, v30
	v_ashrrev_i32_e32 v2, 6, v30
	v_or_b32_e32 v5, s20, v52
	v_ashrrev_i32_e32 v46, 1, v30
	v_lshl_add_u32 v116, v2, 4, v5
	v_lshl_add_u32 v4, s0, 8, v46
	v_mad_i64_i32 v[118:119], s[0:1], v116, s92, v[14:15]
	v_ashrrev_i32_e32 v5, 31, v4
	v_readlane_b32 s0, v244, 50
	v_and_b32_e32 v50, 1, v30
	v_lshlrev_b64 v[4:5], 10, v[4:5]
	v_readlane_b32 s1, v244, 51
	v_bfe_u32 v47, v30, 4, 2
	v_lshlrev_b32_e32 v44, 6, v50
	v_lshl_add_u64 v[4:5], s[0:1], 0, v[4:5]
	v_lshlrev_b32_e32 v114, 4, v47
	v_lshl_add_u64 v[20:21], v[4:5], 0, v[44:45]
	v_lshl_add_u64 v[120:121], v[118:119], 0, v[114:115]
	s_waitcnt vmcnt(16)
	v_mov_b64_e32 v[4:5], v[156:157]
	v_mov_b64_e32 v[6:7], v[158:159]
	v_mov_b64_e32 v[12:13], v[160:161]
	v_mov_b64_e32 v[14:15], v[162:163]
	v_mov_b64_e32 v[16:17], v[164:165]
	v_mov_b64_e32 v[18:19], v[166:167]
	v_mov_b64_e32 v[8:9], v[172:173]
	v_mov_b64_e32 v[10:11], v[174:175]
	v_mov_b64_e32 v[28:29], v[176:177]
	v_mov_b64_e32 v[30:31], v[178:179]
	v_mov_b64_e32 v[32:33], v[196:197]
	v_mov_b64_e32 v[34:35], v[198:199]
	v_mov_b64_e32 v[36:37], v[200:201]
	v_mov_b64_e32 v[38:39], v[202:203]
	v_mov_b64_e32 v[40:41], v[204:205]
	v_mov_b64_e32 v[42:43], v[206:207]
	s_nop 0
	v_mov_b64_e32 v[20:21], v[208:209]
	v_mov_b64_e32 v[22:23], v[210:211]
	v_mov_b64_e32 v[24:25], v[212:213]
	v_mov_b64_e32 v[26:27], v[214:215]
	v_readlane_b32 s0, v243, 0
	v_mul_lo_u32 v45, v46, s97
	s_and_b32 s0, s0, 7
	v_add_u32_e32 v48, 0, v45
	s_lshl_b32 s2, s0, 18
	v_add_u32_e32 v132, v48, v44
	v_mad_u64_u32 v[48:49], s[0:1], v46, s98, v[48:49]
	v_mul_u32_u24_e32 v45, 0x4200, v50
	v_lshlrev_b32_e32 v50, 7, v50
	v_mul_lo_u32 v131, v2, s93
	v_lshlrev_b32_e32 v2, 3, v47
	v_lshl_add_u64 v[122:123], s[10:11], 0, v[50:51]
	v_lshlrev_b32_e32 v50, 5, v47
	v_or_b32_e32 v47, 16, v52
	s_movk_i32 s0, 0x210
	v_lshl_add_u64 v[124:125], s[8:9], 0, v[50:51]
	global_load_dwordx4 v[224:227], v[124:125], off
	global_load_dwordx4 v[228:231], v[124:125], off offset:128
	global_load_dwordx4 v[232:235], v[124:125], off offset:16
	global_load_dwordx4 v[236:239], v[124:125], off offset:144
	v_mul_u32_u24_e32 v51, 0x210, v47
	v_mad_u32_u24 v47, v52, s0, v131
	v_add3_u32 v134, v47, v2, s96
	v_ashrrev_i32_e32 v47, 31, v46
	v_lshlrev_b64 v[46:47], 10, v[46:47]
	v_add_u32_e32 v49, 0, v114
	s_mov_b32 s1, s3
	v_lshl_add_u64 v[46:47], s[2:3], 0, v[46:47]
	v_mov_b32_e32 v133, v49
	v_mul_u32_u24_e32 v50, 0x90, v52
	v_writelane_b32 v244, s0, 62
	v_or_b32_e32 v46, v46, v44
	v_mul_u32_u24_e32 v115, 0x210, v52
	v_ashrrev_i32_e32 v117, 31, v116
	v_writelane_b32 v244, s1, 63
	v_lshl_add_u64 v[126:127], s[6:7], 0, v[46:47]
	s_mov_b64 s[0:1], 64
	v_and_b32_e32 v241, 24, v48
	v_and_b32_e32 v242, 32, v48
	v_and_b32_e32 v48, 0xffffffc7, v48
	v_lshlrev_b32_e32 v241, 1, v241
	v_lshrrev_b32_e32 v242, 2, v242
	v_or3_b32 v48, v48, v241, v242
	v_add_u32_e32 v135, v48, v45
	v_add_u32_e32 v136, v49, v50
	v_add_u32_e32 v137, v133, v51
	v_add_u32_e32 v240, v133, v115
	v_add_u32_e32 v240, 0x9000, v240
	v_add_u32_e32 v241, 0x9000, v137
	v_add_u32_e32 v242, 0xb000, v137
	v_add_u32_e32 v245, 0xd000, v137
	s_branch .LBB0_210

.LBB0_215:
	s_waitcnt vmcnt(0)
	s_mov_b64 s[0:1], 0x1000
	v_lshl_add_u64 v[16:17], v[118:119], 0, s[0:1]
	v_lshl_add_u64 v[4:5], v[16:17], 0, v[2:3]
	v_mov_b64_e32 v[50:51], v[4:5]
	global_load_dwordx2 v[8:9], v[4:5], off
	v_readlane_b32 s4, v244, 0
	v_readlane_b32 s8, v244, 4
	v_readlane_b32 s9, v244, 5
	v_mov_b32_e32 v14, v130
	s_nop 1
	v_permlane16_swap_b32 v14, v130
	v_readlane_b32 s5, v244, 1
	v_readlane_b32 s6, v244, 2
	v_readlane_b32 s7, v244, 3
	v_readlane_b32 s4, v244, 57
	global_load_dwordx4 v[4:7], v114, s[8:9] offset:3072
	global_load_dwordx2 v[52:53], v[50:51], off offset:32
	global_load_dwordx2 v[54:55], v[50:51], off offset:64
	global_load_dwordx2 v[56:57], v[50:51], off offset:96
	global_load_dwordx4 v[58:61], v114, s[8:9] offset:3136
	global_load_dwordx4 v[62:65], v114, s[8:9] offset:3200
	global_load_dwordx4 v[66:69], v114, s[8:9] offset:3264
	global_load_dwordx2 v[70:71], v[50:51], off offset:128
	global_load_dwordx4 v[72:75], v114, s[8:9] offset:3328
	global_load_dwordx2 v[76:77], v[50:51], off offset:160
	global_load_dwordx2 v[78:79], v[50:51], off offset:192
	global_load_dwordx2 v[80:81], v[50:51], off offset:224
	global_load_dwordx4 v[82:85], v114, s[8:9] offset:3392
	global_load_dwordx4 v[86:89], v114, s[8:9] offset:3456
	global_load_dwordx4 v[90:93], v114, s[8:9] offset:3520
	global_load_dwordx2 v[94:95], v[50:51], off offset:256
	global_load_dwordx4 v[96:99], v114, s[8:9] offset:3584
	global_load_dwordx2 v[100:101], v[50:51], off offset:288
	global_load_dwordx2 v[102:103], v[50:51], off offset:320
	global_load_dwordx2 v[104:105], v[50:51], off offset:352
	global_load_dwordx4 v[106:109], v114, s[8:9] offset:3648
	global_load_dwordx4 v[120:123], v114, s[8:9] offset:3712
	global_load_dwordx4 v[124:127], v114, s[8:9] offset:3776
	global_load_dwordx2 v[110:111], v[50:51], off offset:384
	global_load_dwordx4 v[132:135], v114, s[8:9] offset:3840
	global_load_dwordx2 v[136:137], v[50:51], off offset:416
	global_load_dwordx2 v[138:139], v[50:51], off offset:448
	global_load_dwordx2 v[140:141], v[50:51], off offset:480
	global_load_dwordx4 v[142:145], v114, s[8:9] offset:3904
	global_load_dwordx4 v[146:149], v114, s[8:9] offset:3968
	global_load_dwordx4 v[150:153], v114, s[8:9] offset:4032
	v_readlane_b32 s24, v244, 16
	v_readlane_b32 s25, v244, 17
	v_readlane_b32 s26, v244, 42
	v_readlane_b32 s27, v244, 43
	v_readlane_b32 s28, v244, 44
	v_readlane_b32 s29, v244, 45
	v_readlane_b32 s30, v244, 10
	v_readlane_b32 s31, v244, 11
	v_readlane_b32 s32, v244, 14
	v_readlane_b32 s33, v244, 15
	v_readlane_b32 s34, v244, 48
	v_readlane_b32 s35, v244, 49
	v_lshlrev_b32_e32 v113, 2, v0
	v_and_b32_e32 v129, 63, v0
	v_lshrrev_b32_e32 v179, 6, v0
	v_lshlrev_b32_e32 v129, 4, v129
	v_add_u32_e32 v128, 0x1000, v113
	v_lshl_add_u32 v129, v179, 13, v129
	s_add_u32 s36, s34, 0x10000
	s_addc_u32 s37, s35, 0
	v_add_u32_e32 v179, 0x1000, v129
	global_load_dword v154, v113, s[24:25]
	global_load_dword v155, v113, s[26:27]
	global_load_dword v168, v113, s[26:27] offset:2048
	global_load_dword v169, v128, s[26:27]
	global_load_dword v171, v128, s[26:27] offset:2048
	global_load_dword v240, v113, s[28:29]
	global_load_dword v241, v113, s[30:31]
	global_load_dword v242, v113, s[32:33]
	global_load_dwordx4 v[156:159], v129, s[34:35]
	global_load_dwordx4 v[160:163], v129, s[34:35] offset:1024
	global_load_dwordx4 v[164:167], v129, s[34:35] offset:2048
	global_load_dwordx4 v[172:175], v129, s[34:35] offset:3072
	global_load_dwordx4 v[196:199], v129, s[36:37]
	global_load_dwordx4 v[200:203], v129, s[36:37] offset:1024
	global_load_dwordx4 v[204:207], v129, s[36:37] offset:2048
	global_load_dwordx4 v[208:211], v129, s[36:37] offset:3072
	global_load_dwordx4 v[212:215], v179, s[34:35]
	global_load_dwordx4 v[216:219], v179, s[36:37]
	global_load_dwordx4 v[220:223], v179, s[34:35] offset:1024
	global_load_dwordx4 v[224:227], v179, s[36:37] offset:1024
	global_load_dwordx4 v[228:231], v179, s[34:35] offset:2048
	global_load_dwordx4 v[232:235], v179, s[36:37] offset:2048
	global_load_dwordx4 v[236:239], v179, s[34:35] offset:3072
	global_load_dwordx4 v[248:251], v179, s[36:37] offset:3072
	s_waitcnt lgkmcnt(0)
	v_add_f32_e32 v14, v130, v14
	v_mov_b32_e32 v15, v14
	s_nop 1
	v_permlane32_swap_b32 v15, v14
	v_lshlrev_b64 v[10:11], 11, v[116:117]
	v_readlane_b32 s6, v244, 59
	v_readlane_b32 s7, v244, 60
	v_add_u32_e32 v12, s96, v131
	s_mov_b64 s[0:1], 0xdde0600
	v_or_b32_e32 v22, 32, v2
	v_mov_b32_e32 v23, v3
	v_or_b32_e32 v24, 64, v2
	v_mov_b32_e32 v25, v3
	v_or_b32_e32 v18, 0x60, v2
	v_mov_b32_e32 v19, v3
	v_lshl_add_u64 v[10:11], s[6:7], 0, v[10:11]
	s_waitcnt lgkmcnt(0)
	v_add_f32_e32 v14, v14, v15
	v_add3_u32 v26, v12, v115, v2
	v_lshl_add_u64 v[12:13], v[10:11], 0, s[0:1]
	v_lshl_add_u64 v[10:11], v[16:17], 0, v[22:23]
	v_lshl_add_u64 v[20:21], v[16:17], 0, v[24:25]
	v_lshl_add_u64 v[32:33], v[16:17], 0, v[18:19]
	v_fmamk_f32 v14, v14, 0x3b800000, v180
	s_mov_b32 s0, 0x800000
	ds_read2_b64 v[28:31], v26 offset1:4
	s_nop 0
	s_nop 0
	v_mul_f32_e32 v15, 0x4b800000, v14
	v_cmp_gt_f32_e32 vcc, s0, v14
	v_lshl_add_u64 v[34:35], v[12:13], 0, v[2:3]
	s_waitcnt lgkmcnt(0)
	v_lshlrev_b32_e32 v33, 16, v28
	v_cndmask_b32_e32 v14, v14, v15, vcc
	v_rsq_f32_e32 v14, v14
	v_and_b32_e32 v39, 0xffff0000, v28
	v_lshlrev_b32_e32 v41, 16, v29
	v_and_b32_e32 v29, 0xffff0000, v29
	v_mul_f32_e32 v15, 0x45800000, v14
	v_cndmask_b32_e32 v15, v14, v15, vcc
	v_lshl_add_u64 v[18:19], v[12:13], 0, v[18:19]
	v_mov_b32_e32 v44, v15
	v_mov_b32_e32 v46, v15
	v_mov_b32_e32 v48, v15
	v_readlane_b32 s36, v244, 10
	v_readlane_b32 s42, v244, 16
	v_readlane_b32 s43, v244, 17
	v_readlane_b32 s10, v244, 6
	v_readlane_b32 s11, v244, 7
	v_readlane_b32 s5, v244, 58
	s_movk_i32 s0, 0x1000
	v_readlane_b32 s37, v244, 11
	v_readlane_b32 s40, v244, 14
	v_readlane_b32 s41, v244, 15
	s_mov_b32 s3, 0x7f800000
	s_mov_b32 s2, 0x33800000
	v_readlane_b32 s38, v244, 12
	v_readlane_b32 s39, v244, 13
	v_readlane_b32 s44, v244, 18
	v_readlane_b32 s45, v244, 19
	v_readlane_b32 s46, v244, 20
	v_readlane_b32 s47, v244, 21
	v_readlane_b32 s48, v244, 22
	v_readlane_b32 s49, v244, 23
	v_readlane_b32 s50, v244, 24
	v_readlane_b32 s51, v244, 25
	s_waitcnt vmcnt(55)
	v_lshlrev_b32_e32 v32, 16, v8
	v_and_b32_e32 v38, 0xffff0000, v8
	v_mul_f32_e32 v8, 0xbfb8aa3b, v32
	v_exp_f32_e32 v8, v8
	v_lshlrev_b32_e32 v40, 16, v9
	v_and_b32_e32 v28, 0xffff0000, v9
	v_mul_f32_e32 v9, 0xbfb8aa3b, v38
	v_exp_f32_e32 v9, v9
	v_add_f32_e32 v8, 1.0, v8
	v_rcp_f32_e32 v14, v8
	v_mul_f32_e32 v27, 0xbfb8aa3b, v40
	v_exp_f32_e32 v27, v27
	v_add_f32_e32 v43, 1.0, v9
	v_pk_mul_f32 v[8:9], v[14:15], v[32:33]
	v_rcp_f32_e32 v14, v43
	v_mul_f32_e32 v42, 0xbfb8aa3b, v28
	v_exp_f32_e32 v42, v42
	v_add_f32_e32 v27, 1.0, v27
	v_pk_mul_f32 v[32:33], v[14:15], v[38:39]
	v_rcp_f32_e32 v14, v27
	s_waitcnt vmcnt(54)
	v_mul_f32_e32 v4, v4, v9
	v_add_f32_e32 v42, 1.0, v42
	v_mul_f32_e32 v8, v8, v4
	v_mul_f32_e32 v4, v5, v33
	v_mul_f32_e32 v9, v32, v4
	v_pk_mul_f32 v[4:5], v[14:15], v[40:41]
	v_rcp_f32_e32 v14, v42
	v_mul_f32_e32 v5, v6, v5
	v_mul_f32_e32 v6, v4, v5
	v_cvt_pk_bf16_f32 v8, v8, v9
	v_pk_mul_f32 v[4:5], v[14:15], v[28:29]
	s_waitcnt vmcnt(53)
	v_and_b32_e32 v29, 0xffff0000, v52
	v_mul_f32_e32 v5, v7, v5
	v_mul_f32_e32 v4, v4, v5
	v_cvt_pk_bf16_f32 v9, v6, v4
	global_store_dwordx2 v[34:35], v[8:9], off
	v_lshl_add_u64 v[8:9], v[12:13], 0, v[22:23]
	v_lshlrev_b32_e32 v23, 16, v52
	v_lshlrev_b32_e32 v22, 16, v30
	v_and_b32_e32 v28, 0xffff0000, v30
	v_lshlrev_b32_e32 v30, 16, v31
	v_and_b32_e32 v32, 0xffff0000, v31
	v_lshlrev_b32_e32 v31, 16, v53
	v_and_b32_e32 v33, 0xffff0000, v53
	v_mul_f32_e32 v10, 0xbfb8aa3b, v23
	v_mul_f32_e32 v11, 0xbfb8aa3b, v29
	v_mul_f32_e32 v14, 0xbfb8aa3b, v31
	v_mul_f32_e32 v27, 0xbfb8aa3b, v33
	v_exp_f32_e32 v10, v10
	v_exp_f32_e32 v11, v11
	v_exp_f32_e32 v14, v14
	v_exp_f32_e32 v27, v27
	v_add_f32_e32 v10, 1.0, v10
	v_add_f32_e32 v11, 1.0, v11
	v_add_f32_e32 v14, 1.0, v14
	v_add_f32_e32 v27, 1.0, v27
	v_rcp_f32_e32 v35, v10
	v_rcp_f32_e32 v39, v11
	v_rcp_f32_e32 v41, v14
	v_rcp_f32_e32 v43, v27
	v_mov_b32_e32 v34, v15
	v_mov_b32_e32 v38, v15
	v_mov_b32_e32 v40, v15
	v_mov_b32_e32 v42, v15
	v_pk_mul_f32 v[10:11], v[34:35], v[22:23]
	v_pk_mul_f32 v[22:23], v[38:39], v[28:29]
	v_pk_mul_f32 v[28:29], v[40:41], v[30:31]
	v_pk_mul_f32 v[30:31], v[42:43], v[32:33]
	v_mov_b32_e32 v32, v15
	s_waitcnt vmcnt(51)
	v_mul_f32_e32 v4, v58, v10
	v_mul_f32_e32 v5, v59, v22
	v_mul_f32_e32 v6, v60, v28
	v_mul_f32_e32 v7, v61, v30
	v_mul_f32_e32 v4, v4, v11
	v_mul_f32_e32 v5, v5, v23
	v_mul_f32_e32 v6, v6, v29
	v_mul_f32_e32 v7, v7, v31
	v_cvt_pk_bf16_f32 v4, v4, v5
	v_cvt_pk_bf16_f32 v5, v6, v7
	global_store_dwordx2 v[8:9], v[4:5], off
	ds_read2_b64 v[4:7], v26 offset0:8 offset1:12
	v_lshlrev_b32_e32 v29, 16, v55
	v_lshl_add_u64 v[22:23], v[12:13], 0, v[24:25]
	v_lshlrev_b32_e32 v25, 16, v54
	v_and_b32_e32 v31, 0xffff0000, v55
	s_waitcnt lgkmcnt(0)
	v_lshlrev_b32_e32 v28, 16, v5
	v_and_b32_e32 v30, 0xffff0000, v5
	v_and_b32_e32 v5, 0xffff0000, v54
	v_mul_f32_e32 v27, 0xbfb8aa3b, v5
	v_mul_f32_e32 v33, 0xbfb8aa3b, v29
	v_mul_f32_e32 v14, 0xbfb8aa3b, v25
	v_mul_f32_e32 v35, 0xbfb8aa3b, v31
	v_exp_f32_e32 v27, v27
	v_exp_f32_e32 v33, v33
	v_exp_f32_e32 v14, v14
	v_exp_f32_e32 v35, v35
	v_add_f32_e32 v27, 1.0, v27
	v_add_f32_e32 v36, 1.0, v33
	v_add_f32_e32 v14, 1.0, v14
	v_add_f32_e32 v37, 1.0, v35
	v_rcp_f32_e32 v35, v27
	v_rcp_f32_e32 v39, v36
	v_rcp_f32_e32 v33, v14
	v_rcp_f32_e32 v41, v37
	v_lshlrev_b32_e32 v24, 16, v4
	v_and_b32_e32 v4, 0xffff0000, v4
	v_pk_mul_f32 v[4:5], v[34:35], v[4:5]
	v_pk_mul_f32 v[28:29], v[38:39], v[28:29]
	v_pk_mul_f32 v[24:25], v[32:33], v[24:25]
	v_pk_mul_f32 v[30:31], v[40:41], v[30:31]
	v_mov_b32_e32 v36, v15
	s_waitcnt vmcnt(51)
	v_mul_f32_e32 v4, v63, v4
	v_mul_f32_e32 v9, v64, v28
	v_mul_f32_e32 v8, v62, v24
	v_mul_f32_e32 v10, v65, v30
	v_mul_f32_e32 v4, v4, v5
	v_mul_f32_e32 v5, v9, v29
	v_mul_f32_e32 v8, v8, v25
	v_mul_f32_e32 v9, v10, v31
	v_cvt_pk_bf16_f32 v4, v8, v4
	v_cvt_pk_bf16_f32 v5, v5, v9
	global_store_dwordx2 v[22:23], v[4:5], off
	v_or_b32_e32 v10, 0x80, v2
	v_mov_b32_e32 v11, v3
	v_lshl_add_u64 v[4:5], v[16:17], 0, v[10:11]
	v_lshlrev_b32_e32 v28, 16, v7
	v_and_b32_e32 v30, 0xffff0000, v7
	v_lshlrev_b32_e32 v5, 16, v56
	v_and_b32_e32 v7, 0xffff0000, v56
	v_lshlrev_b32_e32 v29, 16, v57
	v_and_b32_e32 v31, 0xffff0000, v57
	v_mul_f32_e32 v14, 0xbfb8aa3b, v5
	v_mul_f32_e32 v20, 0xbfb8aa3b, v7
	v_mul_f32_e32 v21, 0xbfb8aa3b, v29
	v_mul_f32_e32 v27, 0xbfb8aa3b, v31
	v_exp_f32_e32 v14, v14
	v_exp_f32_e32 v20, v20
	v_exp_f32_e32 v21, v21
	v_exp_f32_e32 v27, v27
	v_add_f32_e32 v14, 1.0, v14
	v_add_f32_e32 v20, 1.0, v20
	v_add_f32_e32 v21, 1.0, v21
	v_add_f32_e32 v27, 1.0, v27
	v_rcp_f32_e32 v33, v14
	v_rcp_f32_e32 v35, v20
	v_rcp_f32_e32 v37, v21
	v_rcp_f32_e32 v39, v27
	v_lshlrev_b32_e32 v4, 16, v6
	v_and_b32_e32 v6, 0xffff0000, v6
	v_pk_mul_f32 v[4:5], v[32:33], v[4:5]
	v_pk_mul_f32 v[6:7], v[34:35], v[6:7]
	v_pk_mul_f32 v[20:21], v[36:37], v[28:29]
	v_pk_mul_f32 v[28:29], v[38:39], v[30:31]
	v_lshl_add_u64 v[10:11], v[12:13], 0, v[10:11]
	s_waitcnt vmcnt(51)
	v_mul_f32_e32 v4, v66, v4
	v_mul_f32_e32 v6, v67, v6
	v_mul_f32_e32 v14, v68, v20
	v_mul_f32_e32 v20, v69, v28
	v_mul_f32_e32 v4, v4, v5
	v_mul_f32_e32 v5, v6, v7
	v_mul_f32_e32 v6, v14, v21
	v_mul_f32_e32 v7, v20, v29
	v_cvt_pk_bf16_f32 v4, v4, v5
	v_cvt_pk_bf16_f32 v5, v6, v7
	global_store_dwordx2 v[18:19], v[4:5], off
	ds_read2_b64 v[28:31], v26 offset0:16 offset1:20
	v_or_b32_e32 v22, 0xa0, v2
	v_mov_b32_e32 v23, v3
	v_or_b32_e32 v24, 0xc0, v2
	v_mov_b32_e32 v25, v3
	v_or_b32_e32 v18, 0xe0, v2
	v_mov_b32_e32 v19, v3
	v_lshl_add_u64 v[20:21], v[16:17], 0, v[22:23]
	v_lshl_add_u64 v[32:33], v[16:17], 0, v[24:25]
	v_lshl_add_u64 v[34:35], v[16:17], 0, v[18:19]
	s_nop 0
	s_nop 0
	s_waitcnt lgkmcnt(0)
	v_lshlrev_b32_e32 v38, 16, v29
	v_and_b32_e32 v40, 0xffff0000, v29
	s_waitcnt vmcnt(51)
	v_lshlrev_b32_e32 v35, 16, v70
	v_and_b32_e32 v29, 0xffff0000, v70
	v_lshlrev_b32_e32 v39, 16, v71
	v_and_b32_e32 v41, 0xffff0000, v71
	v_mul_f32_e32 v8, 0xbfb8aa3b, v35
	v_mul_f32_e32 v9, 0xbfb8aa3b, v29
	v_mul_f32_e32 v14, 0xbfb8aa3b, v39
	v_mul_f32_e32 v27, 0xbfb8aa3b, v41
	v_exp_f32_e32 v8, v8
	v_exp_f32_e32 v9, v9
	v_exp_f32_e32 v14, v14
	v_exp_f32_e32 v27, v27
	v_add_f32_e32 v8, 1.0, v8
	v_add_f32_e32 v9, 1.0, v9
	v_add_f32_e32 v14, 1.0, v14
	v_add_f32_e32 v27, 1.0, v27
	v_rcp_f32_e32 v43, v8
	v_rcp_f32_e32 v45, v9
	v_rcp_f32_e32 v47, v14
	v_rcp_f32_e32 v49, v27
	v_lshlrev_b32_e32 v34, 16, v28
	v_and_b32_e32 v28, 0xffff0000, v28
	v_pk_mul_f32 v[8:9], v[42:43], v[34:35]
	v_pk_mul_f32 v[28:29], v[44:45], v[28:29]
	v_pk_mul_f32 v[34:35], v[46:47], v[38:39]
	v_pk_mul_f32 v[38:39], v[48:49], v[40:41]
	v_mov_b32_e32 v40, v15
	v_lshl_add_u64 v[18:19], v[12:13], 0, v[18:19]
	s_waitcnt vmcnt(50)
	v_mul_f32_e32 v4, v72, v8
	v_mul_f32_e32 v5, v73, v28
	v_mul_f32_e32 v6, v74, v34
	v_mul_f32_e32 v7, v75, v38
	v_mul_f32_e32 v4, v4, v9
	v_mul_f32_e32 v5, v5, v29
	v_mul_f32_e32 v6, v6, v35
	v_mul_f32_e32 v7, v7, v39
	v_cvt_pk_bf16_f32 v4, v4, v5
	v_cvt_pk_bf16_f32 v5, v6, v7
	global_store_dwordx2 v[10:11], v[4:5], off
	v_lshl_add_u64 v[8:9], v[12:13], 0, v[22:23]
	s_waitcnt vmcnt(50)
	v_lshlrev_b32_e32 v11, 16, v76
	v_and_b32_e32 v23, 0xffff0000, v76
	v_lshlrev_b32_e32 v10, 16, v30
	v_and_b32_e32 v22, 0xffff0000, v30
	v_lshlrev_b32_e32 v28, 16, v31
	v_and_b32_e32 v30, 0xffff0000, v31
	v_lshlrev_b32_e32 v29, 16, v77
	v_and_b32_e32 v31, 0xffff0000, v77
	v_mul_f32_e32 v14, 0xbfb8aa3b, v11
	v_mul_f32_e32 v27, 0xbfb8aa3b, v23
	v_mul_f32_e32 v35, 0xbfb8aa3b, v29
	v_mul_f32_e32 v36, 0xbfb8aa3b, v31
	v_exp_f32_e32 v14, v14
	v_exp_f32_e32 v27, v27
	v_exp_f32_e32 v35, v35
	v_exp_f32_e32 v36, v36
	v_add_f32_e32 v14, 1.0, v14
	v_add_f32_e32 v27, 1.0, v27
	v_add_f32_e32 v37, 1.0, v35
	v_add_f32_e32 v36, 1.0, v36
	v_rcp_f32_e32 v35, v14
	v_rcp_f32_e32 v39, v27
	v_rcp_f32_e32 v41, v37
	v_rcp_f32_e32 v43, v36
	v_mov_b32_e32 v34, v15
	v_mov_b32_e32 v38, v15
	v_pk_mul_f32 v[10:11], v[34:35], v[10:11]
	v_pk_mul_f32 v[22:23], v[38:39], v[22:23]
	v_pk_mul_f32 v[28:29], v[40:41], v[28:29]
	v_pk_mul_f32 v[30:31], v[42:43], v[30:31]
	v_mov_b32_e32 v36, v15
	s_waitcnt vmcnt(47)
	v_mul_f32_e32 v4, v82, v10
	v_mul_f32_e32 v5, v83, v22
	v_mul_f32_e32 v6, v84, v28
	v_mul_f32_e32 v7, v85, v30
	v_mul_f32_e32 v4, v4, v11
	v_mul_f32_e32 v5, v5, v23
	v_mul_f32_e32 v6, v6, v29
	v_mul_f32_e32 v7, v7, v31
	v_cvt_pk_bf16_f32 v4, v4, v5
	v_cvt_pk_bf16_f32 v5, v6, v7
	global_store_dwordx2 v[8:9], v[4:5], off
	ds_read2_b64 v[4:7], v26 offset0:24 offset1:28
	v_lshlrev_b32_e32 v29, 16, v79
	v_lshl_add_u64 v[22:23], v[12:13], 0, v[24:25]
	v_lshlrev_b32_e32 v25, 16, v78
	v_and_b32_e32 v31, 0xffff0000, v79
	s_waitcnt lgkmcnt(0)
	v_lshlrev_b32_e32 v28, 16, v5
	v_and_b32_e32 v30, 0xffff0000, v5
	v_and_b32_e32 v5, 0xffff0000, v78
	v_mul_f32_e32 v27, 0xbfb8aa3b, v5
	v_mul_f32_e32 v32, 0xbfb8aa3b, v29
	v_mul_f32_e32 v14, 0xbfb8aa3b, v25
	v_mul_f32_e32 v33, 0xbfb8aa3b, v31
	v_exp_f32_e32 v27, v27
	v_exp_f32_e32 v32, v32
	v_exp_f32_e32 v14, v14
	v_exp_f32_e32 v33, v33
	v_add_f32_e32 v27, 1.0, v27
	v_add_f32_e32 v32, 1.0, v32
	v_add_f32_e32 v14, 1.0, v14
	v_add_f32_e32 v33, 1.0, v33
	v_rcp_f32_e32 v37, v27
	v_rcp_f32_e32 v39, v32
	v_rcp_f32_e32 v35, v14
	v_rcp_f32_e32 v41, v33
	v_lshlrev_b32_e32 v24, 16, v4
	v_and_b32_e32 v4, 0xffff0000, v4
	v_pk_mul_f32 v[4:5], v[36:37], v[4:5]
	v_pk_mul_f32 v[28:29], v[38:39], v[28:29]
	v_pk_mul_f32 v[24:25], v[34:35], v[24:25]
	v_pk_mul_f32 v[30:31], v[40:41], v[30:31]
	v_mov_b32_e32 v32, v15
	s_waitcnt vmcnt(47)
	v_mul_f32_e32 v4, v87, v4
	v_mul_f32_e32 v9, v88, v28
	v_mul_f32_e32 v8, v86, v24
	v_mul_f32_e32 v10, v89, v30
	v_mul_f32_e32 v4, v4, v5
	v_mul_f32_e32 v5, v9, v29
	v_mul_f32_e32 v8, v8, v25
	v_mul_f32_e32 v9, v10, v31
	v_cvt_pk_bf16_f32 v4, v8, v4
	v_cvt_pk_bf16_f32 v5, v5, v9
	global_store_dwordx2 v[22:23], v[4:5], off
	v_or_b32_e32 v10, 0x100, v2
	v_mov_b32_e32 v11, v3
	v_lshl_add_u64 v[4:5], v[16:17], 0, v[10:11]
	v_lshlrev_b32_e32 v28, 16, v7
	v_and_b32_e32 v30, 0xffff0000, v7
	v_lshlrev_b32_e32 v5, 16, v80
	v_and_b32_e32 v7, 0xffff0000, v80
	v_lshlrev_b32_e32 v29, 16, v81
	v_and_b32_e32 v31, 0xffff0000, v81
	v_mul_f32_e32 v14, 0xbfb8aa3b, v5
	v_mul_f32_e32 v20, 0xbfb8aa3b, v7
	v_mul_f32_e32 v21, 0xbfb8aa3b, v29
	v_mul_f32_e32 v27, 0xbfb8aa3b, v31
	v_exp_f32_e32 v14, v14
	v_exp_f32_e32 v20, v20
	v_exp_f32_e32 v21, v21
	v_exp_f32_e32 v27, v27
	v_add_f32_e32 v14, 1.0, v14
	v_add_f32_e32 v20, 1.0, v20
	v_add_f32_e32 v21, 1.0, v21
	v_add_f32_e32 v27, 1.0, v27
	v_rcp_f32_e32 v33, v14
	v_rcp_f32_e32 v35, v20
	v_rcp_f32_e32 v37, v21
	v_rcp_f32_e32 v39, v27
	v_lshlrev_b32_e32 v4, 16, v6
	v_and_b32_e32 v6, 0xffff0000, v6
	v_pk_mul_f32 v[4:5], v[32:33], v[4:5]
	v_pk_mul_f32 v[6:7], v[34:35], v[6:7]
	v_pk_mul_f32 v[20:21], v[36:37], v[28:29]
	v_pk_mul_f32 v[28:29], v[38:39], v[30:31]
	v_lshl_add_u64 v[36:37], v[12:13], 0, v[10:11]
	s_waitcnt vmcnt(47)
	v_mul_f32_e32 v4, v90, v4
	v_mul_f32_e32 v6, v91, v6
	v_mul_f32_e32 v14, v92, v20
	v_mul_f32_e32 v20, v93, v28
	v_mul_f32_e32 v4, v4, v5
	v_mul_f32_e32 v5, v6, v7
	v_mul_f32_e32 v6, v14, v21
	v_mul_f32_e32 v7, v20, v29
	v_cvt_pk_bf16_f32 v4, v4, v5
	v_cvt_pk_bf16_f32 v5, v6, v7
	global_store_dwordx2 v[18:19], v[4:5], off
	ds_read2_b64 v[28:31], v26 offset0:32 offset1:36
	v_or_b32_e32 v20, 0x120, v2
	v_mov_b32_e32 v21, v3
	v_or_b32_e32 v22, 0x140, v2
	v_mov_b32_e32 v23, v3
	v_or_b32_e32 v18, 0x160, v2
	v_mov_b32_e32 v19, v3
	v_lshl_add_u64 v[24:25], v[16:17], 0, v[20:21]
	v_lshl_add_u64 v[32:33], v[16:17], 0, v[22:23]
	v_lshl_add_u64 v[34:35], v[16:17], 0, v[18:19]
	s_nop 0
	s_nop 0
	s_waitcnt lgkmcnt(0)
	v_lshlrev_b32_e32 v38, 16, v29
	v_and_b32_e32 v40, 0xffff0000, v29
	s_waitcnt vmcnt(47)
	v_lshlrev_b32_e32 v35, 16, v94
	v_and_b32_e32 v29, 0xffff0000, v94
	v_lshlrev_b32_e32 v39, 16, v95
	v_and_b32_e32 v41, 0xffff0000, v95
	v_mul_f32_e32 v8, 0xbfb8aa3b, v35
	v_mul_f32_e32 v9, 0xbfb8aa3b, v29
	v_mul_f32_e32 v14, 0xbfb8aa3b, v39
	v_mul_f32_e32 v27, 0xbfb8aa3b, v41
	v_exp_f32_e32 v8, v8
	v_exp_f32_e32 v9, v9
	v_exp_f32_e32 v14, v14
	v_exp_f32_e32 v27, v27
	v_add_f32_e32 v8, 1.0, v8
	v_add_f32_e32 v9, 1.0, v9
	v_add_f32_e32 v14, 1.0, v14
	v_add_f32_e32 v27, 1.0, v27
	v_rcp_f32_e32 v43, v8
	v_rcp_f32_e32 v45, v9
	v_rcp_f32_e32 v47, v14
	v_rcp_f32_e32 v49, v27
	v_lshlrev_b32_e32 v34, 16, v28
	v_and_b32_e32 v28, 0xffff0000, v28
	v_pk_mul_f32 v[8:9], v[42:43], v[34:35]
	v_pk_mul_f32 v[28:29], v[44:45], v[28:29]
	v_pk_mul_f32 v[34:35], v[46:47], v[38:39]
	v_pk_mul_f32 v[38:39], v[48:49], v[40:41]
	v_mov_b32_e32 v40, v15
	s_waitcnt vmcnt(46)
	v_mul_f32_e32 v4, v96, v8
	v_mul_f32_e32 v5, v97, v28
	v_mul_f32_e32 v6, v98, v34
	v_mul_f32_e32 v7, v99, v38
	v_mul_f32_e32 v4, v4, v9
	v_mul_f32_e32 v5, v5, v29
	v_mul_f32_e32 v6, v6, v35
	v_mul_f32_e32 v7, v7, v39
	v_cvt_pk_bf16_f32 v4, v4, v5
	v_cvt_pk_bf16_f32 v5, v6, v7
	global_store_dwordx2 v[36:37], v[4:5], off
	v_lshl_add_u64 v[8:9], v[12:13], 0, v[20:21]
	s_waitcnt vmcnt(46)
	v_lshlrev_b32_e32 v21, 16, v100
	v_and_b32_e32 v29, 0xffff0000, v100
	v_lshlrev_b32_e32 v20, 16, v30
	v_and_b32_e32 v28, 0xffff0000, v30
	v_lshlrev_b32_e32 v30, 16, v31
	v_and_b32_e32 v34, 0xffff0000, v31
	v_lshlrev_b32_e32 v31, 16, v101
	v_and_b32_e32 v35, 0xffff0000, v101
	v_mul_f32_e32 v14, 0xbfb8aa3b, v21
	v_mul_f32_e32 v24, 0xbfb8aa3b, v29
	v_mul_f32_e32 v25, 0xbfb8aa3b, v31
	v_mul_f32_e32 v27, 0xbfb8aa3b, v35
	v_exp_f32_e32 v14, v14
	v_exp_f32_e32 v24, v24
	v_exp_f32_e32 v25, v25
	v_exp_f32_e32 v27, v27
	v_add_f32_e32 v14, 1.0, v14
	v_add_f32_e32 v24, 1.0, v24
	v_add_f32_e32 v25, 1.0, v25
	v_add_f32_e32 v27, 1.0, v27
	v_rcp_f32_e32 v37, v14
	v_rcp_f32_e32 v39, v24
	v_rcp_f32_e32 v41, v25
	v_rcp_f32_e32 v43, v27
	v_mov_b32_e32 v36, v15
	v_mov_b32_e32 v38, v15
	v_pk_mul_f32 v[20:21], v[36:37], v[20:21]
	v_pk_mul_f32 v[24:25], v[38:39], v[28:29]
	v_pk_mul_f32 v[28:29], v[40:41], v[30:31]
	v_pk_mul_f32 v[30:31], v[42:43], v[34:35]
	v_mov_b32_e32 v34, v15
	s_waitcnt vmcnt(43)
	v_mul_f32_e32 v4, v106, v20
	v_mul_f32_e32 v5, v107, v24
	v_mul_f32_e32 v6, v108, v28
	v_mul_f32_e32 v7, v109, v30
	v_mul_f32_e32 v4, v4, v21
	v_mul_f32_e32 v5, v5, v25
	v_mul_f32_e32 v6, v6, v29
	v_mul_f32_e32 v7, v7, v31
	v_cvt_pk_bf16_f32 v4, v4, v5
	v_cvt_pk_bf16_f32 v5, v6, v7
	global_store_dwordx2 v[8:9], v[4:5], off
	ds_read2_b64 v[4:7], v26 offset0:40 offset1:44
	v_lshl_add_u64 v[8:9], v[12:13], 0, v[22:23]
	v_lshlrev_b32_e32 v21, 16, v102
	v_lshlrev_b32_e32 v23, 16, v103
	v_and_b32_e32 v25, 0xffff0000, v103
	s_waitcnt lgkmcnt(0)
	v_lshlrev_b32_e32 v22, 16, v5
	v_and_b32_e32 v24, 0xffff0000, v5
	v_and_b32_e32 v5, 0xffff0000, v102
	v_mul_f32_e32 v14, 0xbfb8aa3b, v21
	v_mul_f32_e32 v27, 0xbfb8aa3b, v5
	v_mul_f32_e32 v32, 0xbfb8aa3b, v23
	v_mul_f32_e32 v33, 0xbfb8aa3b, v25
	v_exp_f32_e32 v14, v14
	v_exp_f32_e32 v27, v27
	v_exp_f32_e32 v32, v32
	v_exp_f32_e32 v33, v33
	v_add_f32_e32 v14, 1.0, v14
	v_add_f32_e32 v27, 1.0, v27
	v_add_f32_e32 v32, 1.0, v32
	v_add_f32_e32 v33, 1.0, v33
	v_rcp_f32_e32 v35, v14
	v_rcp_f32_e32 v37, v27
	v_rcp_f32_e32 v39, v32
	v_rcp_f32_e32 v41, v33
	v_lshlrev_b32_e32 v20, 16, v4
	v_and_b32_e32 v4, 0xffff0000, v4
	v_pk_mul_f32 v[20:21], v[34:35], v[20:21]
	v_pk_mul_f32 v[4:5], v[36:37], v[4:5]
	v_pk_mul_f32 v[22:23], v[38:39], v[22:23]
	v_pk_mul_f32 v[24:25], v[40:41], v[24:25]
	v_mov_b32_e32 v32, v15
	s_waitcnt vmcnt(43)
	v_mul_f32_e32 v14, v120, v20
	v_mul_f32_e32 v4, v121, v4
	v_mul_f32_e32 v20, v122, v22
	v_mul_f32_e32 v22, v123, v24
	v_mul_f32_e32 v4, v4, v5
	v_mul_f32_e32 v5, v20, v23
	v_mul_f32_e32 v14, v14, v21
	v_mul_f32_e32 v20, v22, v25
	v_cvt_pk_bf16_f32 v4, v14, v4
	v_cvt_pk_bf16_f32 v5, v5, v20
	global_store_dwordx2 v[8:9], v[4:5], off
	v_or_b32_e32 v20, 0x180, v2
	v_mov_b32_e32 v21, v3
	v_lshl_add_u64 v[4:5], v[16:17], 0, v[20:21]
	v_lshl_add_u64 v[8:9], v[12:13], 0, v[18:19]
	v_lshlrev_b32_e32 v28, 16, v7
	v_and_b32_e32 v30, 0xffff0000, v7
	v_lshlrev_b32_e32 v5, 16, v104
	v_and_b32_e32 v7, 0xffff0000, v104
	v_lshlrev_b32_e32 v29, 16, v105
	v_and_b32_e32 v31, 0xffff0000, v105
	v_mul_f32_e32 v10, 0xbfb8aa3b, v5
	v_mul_f32_e32 v11, 0xbfb8aa3b, v7
	v_mul_f32_e32 v14, 0xbfb8aa3b, v29
	v_mul_f32_e32 v27, 0xbfb8aa3b, v31
	v_exp_f32_e32 v10, v10
	v_exp_f32_e32 v11, v11
	v_exp_f32_e32 v14, v14
	v_exp_f32_e32 v27, v27
	v_add_f32_e32 v10, 1.0, v10
	v_add_f32_e32 v11, 1.0, v11
	v_add_f32_e32 v14, 1.0, v14
	v_add_f32_e32 v27, 1.0, v27
	v_rcp_f32_e32 v33, v10
	v_rcp_f32_e32 v35, v11
	v_rcp_f32_e32 v37, v14
	v_rcp_f32_e32 v39, v27
	v_lshlrev_b32_e32 v4, 16, v6
	v_and_b32_e32 v6, 0xffff0000, v6
	v_pk_mul_f32 v[4:5], v[32:33], v[4:5]
	v_pk_mul_f32 v[6:7], v[34:35], v[6:7]
	v_pk_mul_f32 v[10:11], v[36:37], v[28:29]
	v_pk_mul_f32 v[28:29], v[38:39], v[30:31]
	v_lshl_add_u64 v[20:21], v[12:13], 0, v[20:21]
	s_waitcnt vmcnt(43)
	v_mul_f32_e32 v4, v124, v4
	v_mul_f32_e32 v6, v125, v6
	v_mul_f32_e32 v10, v126, v10
	v_mul_f32_e32 v14, v127, v28
	v_mul_f32_e32 v4, v4, v5
	v_mul_f32_e32 v5, v6, v7
	v_mul_f32_e32 v6, v10, v11
	v_mul_f32_e32 v7, v14, v29
	v_cvt_pk_bf16_f32 v4, v4, v5
	v_cvt_pk_bf16_f32 v5, v6, v7
	global_store_dwordx2 v[8:9], v[4:5], off
	ds_read2_b64 v[8:11], v26 offset0:48 offset1:52
	s_waitcnt vmcnt(43)
	v_lshlrev_b32_e32 v33, 16, v110
	v_lshlrev_b32_e32 v35, 16, v111
	v_and_b32_e32 v37, 0xffff0000, v111
	v_mul_f32_e32 v14, 0xbfb8aa3b, v33
	s_waitcnt lgkmcnt(0)
	v_lshlrev_b32_e32 v34, 16, v9
	v_and_b32_e32 v36, 0xffff0000, v9
	v_and_b32_e32 v9, 0xffff0000, v110
	v_mul_f32_e32 v18, 0xbfb8aa3b, v9
	v_mul_f32_e32 v19, 0xbfb8aa3b, v35
	v_mul_f32_e32 v27, 0xbfb8aa3b, v37
	v_exp_f32_e32 v14, v14
	v_exp_f32_e32 v18, v18
	v_or_b32_e32 v22, 0x1a0, v2
	v_mov_b32_e32 v23, v3
	v_or_b32_e32 v24, 0x1c0, v2
	v_mov_b32_e32 v25, v3
	v_or_b32_e32 v2, 0x1e0, v2
	v_exp_f32_e32 v19, v19
	v_exp_f32_e32 v27, v27
	v_lshl_add_u64 v[28:29], v[16:17], 0, v[22:23]
	v_lshl_add_u64 v[30:31], v[16:17], 0, v[24:25]
	v_lshl_add_u64 v[16:17], v[16:17], 0, v[2:3]
	s_nop 0
	s_nop 0
	v_add_f32_e32 v14, 1.0, v14
	v_add_f32_e32 v18, 1.0, v18
	v_add_f32_e32 v19, 1.0, v19
	v_add_f32_e32 v27, 1.0, v27
	v_rcp_f32_e32 v39, v14
	v_rcp_f32_e32 v41, v18
	v_rcp_f32_e32 v43, v19
	v_rcp_f32_e32 v45, v27
	v_lshlrev_b32_e32 v32, 16, v8
	v_and_b32_e32 v8, 0xffff0000, v8
	v_pk_mul_f32 v[18:19], v[38:39], v[32:33]
	v_pk_mul_f32 v[8:9], v[40:41], v[8:9]
	v_pk_mul_f32 v[32:33], v[42:43], v[34:35]
	v_pk_mul_f32 v[34:35], v[44:45], v[36:37]
	v_mov_b32_e32 v36, v15
	v_mov_b32_e32 v42, v0
	s_waitcnt vmcnt(42)
	v_mul_f32_e32 v4, v132, v18
	v_mul_f32_e32 v5, v133, v8
	v_mul_f32_e32 v6, v134, v32
	v_mul_f32_e32 v7, v135, v34
	v_mul_f32_e32 v4, v4, v19
	v_mul_f32_e32 v5, v5, v9
	v_mul_f32_e32 v6, v6, v33
	v_mul_f32_e32 v7, v7, v35
	v_cvt_pk_bf16_f32 v4, v4, v5
	v_cvt_pk_bf16_f32 v5, v6, v7
	global_store_dwordx2 v[20:21], v[4:5], off
	v_lshl_add_u64 v[8:9], v[12:13], 0, v[22:23]
	v_lshlrev_b32_e32 v20, 16, v11
	v_and_b32_e32 v22, 0xffff0000, v11
	v_lshlrev_b32_e32 v18, 16, v10
	v_and_b32_e32 v10, 0xffff0000, v10
	v_mov_b32_e32 v32, v15
	v_mov_b32_e32 v34, v15
	s_waitcnt vmcnt(42)
	v_lshlrev_b32_e32 v19, 16, v136
	v_and_b32_e32 v11, 0xffff0000, v136
	v_lshlrev_b32_e32 v21, 16, v137
	v_and_b32_e32 v23, 0xffff0000, v137
	v_mul_f32_e32 v14, 0xbfb8aa3b, v19
	v_mul_f32_e32 v27, 0xbfb8aa3b, v11
	v_mul_f32_e32 v28, 0xbfb8aa3b, v21
	v_mul_f32_e32 v29, 0xbfb8aa3b, v23
	v_exp_f32_e32 v14, v14
	v_exp_f32_e32 v27, v27
	v_exp_f32_e32 v28, v28
	v_exp_f32_e32 v29, v29
	v_add_f32_e32 v14, 1.0, v14
	v_add_f32_e32 v27, 1.0, v27
	v_add_f32_e32 v28, 1.0, v28
	v_add_f32_e32 v29, 1.0, v29
	v_rcp_f32_e32 v33, v14
	v_rcp_f32_e32 v35, v27
	v_rcp_f32_e32 v37, v28
	v_rcp_f32_e32 v39, v29
	v_pk_mul_f32 v[18:19], v[32:33], v[18:19]
	v_pk_mul_f32 v[10:11], v[34:35], v[10:11]
	v_pk_mul_f32 v[20:21], v[36:37], v[20:21]
	v_pk_mul_f32 v[22:23], v[38:39], v[22:23]
	v_mov_b32_e32 v28, v15
	s_waitcnt vmcnt(39)
	v_mul_f32_e32 v4, v142, v18
	v_mul_f32_e32 v5, v143, v10
	v_mul_f32_e32 v6, v144, v20
	v_mul_f32_e32 v7, v145, v22
	v_mul_f32_e32 v4, v4, v19
	v_mul_f32_e32 v5, v5, v11
	v_mul_f32_e32 v6, v6, v21
	v_mul_f32_e32 v7, v7, v23
	v_cvt_pk_bf16_f32 v4, v4, v5
	v_cvt_pk_bf16_f32 v5, v6, v7
	global_store_dwordx2 v[8:9], v[4:5], off
	ds_read2_b64 v[4:7], v26 offset0:56 offset1:60
	v_lshl_add_u64 v[18:19], v[12:13], 0, v[24:25]
	v_lshlrev_b32_e32 v23, 16, v139
	v_lshlrev_b32_e32 v21, 16, v138
	v_and_b32_e32 v25, 0xffff0000, v139
	s_waitcnt lgkmcnt(0)
	v_lshlrev_b32_e32 v22, 16, v5
	v_and_b32_e32 v24, 0xffff0000, v5
	v_and_b32_e32 v5, 0xffff0000, v138
	v_mul_f32_e32 v27, 0xbfb8aa3b, v5
	v_mul_f32_e32 v29, 0xbfb8aa3b, v23
	v_mul_f32_e32 v14, 0xbfb8aa3b, v21
	v_mul_f32_e32 v30, 0xbfb8aa3b, v25
	v_exp_f32_e32 v27, v27
	v_exp_f32_e32 v29, v29
	v_exp_f32_e32 v14, v14
	v_exp_f32_e32 v30, v30
	v_add_f32_e32 v31, 1.0, v27
	v_add_f32_e32 v33, 1.0, v29
	v_add_f32_e32 v14, 1.0, v14
	v_add_f32_e32 v30, 1.0, v30
	v_rcp_f32_e32 v29, v31
	v_rcp_f32_e32 v33, v33
	v_rcp_f32_e32 v27, v14
	v_rcp_f32_e32 v35, v30
	v_lshlrev_b32_e32 v20, 16, v4
	v_and_b32_e32 v4, 0xffff0000, v4
	v_mov_b32_e32 v26, v15
	v_pk_mul_f32 v[4:5], v[28:29], v[4:5]
	v_pk_mul_f32 v[22:23], v[32:33], v[22:23]
	v_pk_mul_f32 v[20:21], v[26:27], v[20:21]
	v_pk_mul_f32 v[24:25], v[34:35], v[24:25]
	v_lshlrev_b32_e32 v14, 16, v7
	s_waitcnt vmcnt(39)
	v_mul_f32_e32 v4, v147, v4
	v_mul_f32_e32 v9, v148, v22
	v_mul_f32_e32 v8, v146, v20
	v_mul_f32_e32 v10, v149, v24
	v_mul_f32_e32 v4, v4, v5
	v_mul_f32_e32 v5, v9, v23
	v_mul_f32_e32 v8, v8, v21
	v_mul_f32_e32 v9, v10, v25
	v_cvt_pk_bf16_f32 v4, v8, v4
	v_cvt_pk_bf16_f32 v5, v5, v9
	global_store_dwordx2 v[18:19], v[4:5], off
	v_lshl_add_u64 v[4:5], v[12:13], 0, v[2:3]
	v_and_b32_e32 v18, 0xffff0000, v7
	v_mov_b32_e32 v20, v15
	v_mov_b32_e32 v22, v15
	v_mov_b32_e32 v24, v15
	v_lshlrev_b32_e32 v13, 16, v140
	v_and_b32_e32 v7, 0xffff0000, v140
	v_lshlrev_b32_e32 v15, 16, v141
	v_and_b32_e32 v19, 0xffff0000, v141
	v_mul_f32_e32 v2, 0xbfb8aa3b, v13
	v_mul_f32_e32 v16, 0xbfb8aa3b, v7
	v_mul_f32_e32 v17, 0xbfb8aa3b, v15
	v_mul_f32_e32 v21, 0xbfb8aa3b, v19
	v_exp_f32_e32 v2, v2
	v_exp_f32_e32 v16, v16
	v_exp_f32_e32 v17, v17
	v_exp_f32_e32 v21, v21
	v_add_f32_e32 v2, 1.0, v2
	v_add_f32_e32 v16, 1.0, v16
	v_add_f32_e32 v17, 1.0, v17
	v_add_f32_e32 v27, 1.0, v21
	v_rcp_f32_e32 v21, v2
	v_rcp_f32_e32 v23, v16
	v_rcp_f32_e32 v25, v17
	v_rcp_f32_e32 v27, v27
	v_lshlrev_b32_e32 v12, 16, v6
	v_and_b32_e32 v6, 0xffff0000, v6
	v_pk_mul_f32 v[12:13], v[20:21], v[12:13]
	v_pk_mul_f32 v[6:7], v[22:23], v[6:7]
	v_pk_mul_f32 v[14:15], v[24:25], v[14:15]
	v_pk_mul_f32 v[16:17], v[26:27], v[18:19]
	v_readlane_b32 s4, v244, 32
	v_readlane_b32 s14, v244, 42
	v_readlane_b32 s15, v244, 43
	v_readlane_b32 s16, v244, 44
	v_readlane_b32 s17, v244, 45
	v_readlane_b32 s6, v244, 34
	s_mov_b32 s6, 0xbfb8aa3b
	s_mov_b32 s4, 0x3f2aaaab
	v_readlane_b32 s5, v244, 33
	s_mov_b32 s5, 0x3f317218
	v_readlane_b32 s7, v244, 35
	v_readlane_b32 s8, v244, 36
	v_readlane_b32 s9, v244, 37
	v_readlane_b32 s10, v244, 38
	v_readlane_b32 s11, v244, 39
	v_readlane_b32 s12, v244, 40
	v_readlane_b32 s13, v244, 41
	v_readlane_b32 s18, v244, 46
	v_readlane_b32 s19, v244, 47
	s_waitcnt vmcnt(39)
	v_mul_f32_e32 v2, v150, v12
	v_mul_f32_e32 v6, v151, v6
	v_mul_f32_e32 v8, v152, v14
	v_mul_f32_e32 v9, v153, v16
	v_mul_f32_e32 v6, v6, v7
	v_mul_f32_e32 v7, v8, v15
	v_mul_f32_e32 v2, v2, v13
	v_mul_f32_e32 v8, v9, v17
	v_cvt_pk_bf16_f32 v6, v2, v6
	v_cvt_pk_bf16_f32 v7, v7, v8
	global_store_dwordx2 v[4:5], v[6:7], off
	s_barrier
	s_waitcnt vmcnt(32)
	s_nop 0
	v_ashrrev_i32_e32 v43, 31, v42
	v_lshlrev_b64 v[4:5], 2, v[42:43]
	v_lshl_add_u64 v[6:7], s[42:43], 0, v[4:5]
	v_mov_b32_e32 v2, v154
	v_lshl_add_u64 v[8:9], s[14:15], 0, v[4:5]
	v_add_co_u32_e32 v6, vcc, s0, v8
	v_bfe_u32 v43, v42, 4, 2
	s_nop 0
	v_addc_co_u32_e32 v7, vcc, 0, v9, vcc
	v_mov_b32_e32 v14, v155
	v_mov_b32_e32 v15, v168
	v_mov_b32_e32 v16, v169
	v_mov_b32_e32 v17, v171
	v_and_b32_e32 v18, 0xffffffc0, v42
	v_lshl_or_b32 v104, v43, 3, v18
	v_lshl_add_u64 v[18:19], s[16:17], 0, v[4:5]
	v_lshl_add_u64 v[20:21], s[36:37], 0, v[4:5]
	v_lshl_add_u64 v[4:5], s[40:41], 0, v[4:5]
	v_mov_b32_e32 v18, v240
	s_nop 0
	v_mov_b32_e32 v19, v241
	s_nop 0
	v_mov_b32_e32 v20, v242
	v_lshl_add_u32 v30, v42, 5, 0
	v_and_b32_e32 v195, 15, v42
	v_cmp_lt_u32_e32 vcc, 2, v195
	s_or_b64 s[0:1], s[22:23], vcc
	v_mov_b32_e32 v8, v3
	v_mov_b32_e32 v9, v3
	v_mov_b32_e32 v6, v3
	v_mov_b32_e32 v7, v3
	v_mov_b64_e32 v[12:13], v[8:9]
	v_mov_b64_e32 v[10:11], v[6:7]
	v_ashrrev_i32_e32 v105, 31, v104
	v_mul_f32_e64 v4, |v2|, s6
	v_exp_f32_e32 v21, v4
	v_max_f32_e64 v2, -v2, -v2
	v_max_f32_e32 v2, 0, v2
	ds_write_b128 v30, v[14:17]
	v_add_f32_e32 v14, 1.0, v21
	v_add_f32_e32 v15, -1.0, v14
	v_frexp_mant_f32_e32 v16, v14
	v_cvt_f64_f32_e32 v[4:5], v14
	v_sub_f32_e32 v17, v15, v14
	v_frexp_exp_i32_f64_e32 v4, v[4:5]
	v_cmp_gt_f32_e32 vcc, s4, v16
	v_sub_f32_e32 v15, v21, v15
	v_add_f32_e32 v5, 1.0, v17
	v_subbrev_co_u32_e32 v4, vcc, 0, v4, vcc
	v_add_f32_e32 v5, v15, v5
	v_sub_u32_e32 v15, 0, v4
	v_ldexp_f32 v14, v14, v15
	v_add_f32_e32 v16, -1.0, v14
	v_add_f32_e32 v17, 1.0, v14
	v_ldexp_f32 v5, v5, v15
	v_add_f32_e32 v15, 1.0, v16
	v_add_f32_e32 v22, -1.0, v17
	v_sub_f32_e32 v15, v14, v15
	v_sub_f32_e32 v14, v14, v22
	v_add_f32_e32 v22, v5, v15
	v_add_f32_e32 v5, v5, v14
	v_add_f32_e32 v24, v17, v5
	v_rcp_f32_e32 v25, v24
	v_add_f32_e32 v15, v16, v22
	v_sub_f32_e32 v16, v15, v16
	v_sub_f32_e32 v14, v24, v17
	v_mul_f32_e32 v27, v15, v25
	v_sub_f32_e32 v26, v22, v16
	v_mul_f32_e32 v16, v24, v27
	v_sub_f32_e32 v5, v5, v14
	v_fma_f32 v22, v27, v24, -v16
	v_fmac_f32_e32 v22, v27, v5
	v_add_f32_e32 v14, v16, v22
	v_sub_f32_e32 v17, v15, v14
	v_mov_b32_e32 v23, v14
	v_pk_add_f32 v[14:15], v[14:15], v[16:17] neg_lo:[0,1] neg_hi:[0,1]
	v_cvt_f32_i32_e32 v4, v4
	v_pk_add_f32 v[14:15], v[14:15], v[22:23] neg_lo:[0,1] neg_hi:[0,1]
	v_cmp_neq_f32_e32 vcc, s3, v21
	v_add_f32_e32 v15, v26, v15
	v_add_f32_e32 v14, v14, v15
	v_add_f32_e32 v15, v17, v14
	v_mul_f32_e32 v23, v25, v15
	v_mul_f32_e32 v16, v24, v23
	v_sub_f32_e32 v17, v17, v15
	v_add_f32_e32 v28, v27, v23
	v_fma_f32 v22, v23, v24, -v16
	v_add_f32_e32 v26, v14, v17
	v_sub_f32_e32 v14, v28, v27
	v_fmac_f32_e32 v22, v23, v5
	v_sub_f32_e32 v5, v23, v14
	v_add_f32_e32 v14, v16, v22
	v_sub_f32_e32 v17, v15, v14
	v_mov_b32_e32 v23, v14
	v_pk_add_f32 v[14:15], v[14:15], v[16:17] neg_lo:[0,1] neg_hi:[0,1]
	s_nop 0
	v_pk_add_f32 v[14:15], v[14:15], v[22:23] neg_lo:[0,1] neg_hi:[0,1]
	s_nop 0
	v_add_f32_e32 v15, v26, v15
	v_add_f32_e32 v14, v14, v15
	v_add_f32_e32 v14, v17, v14
	v_mul_f32_e32 v14, v25, v14
	v_add_f32_e32 v5, v5, v14
	v_add_f32_e32 v14, v28, v5
	v_mul_f32_e32 v16, v14, v14
	v_sub_f32_e32 v17, v14, v28
	v_fmamk_f32 v22, v16, 0x3e9b6dac, v181
	v_sub_f32_e32 v17, v5, v17
	v_mul_f32_e32 v5, v14, v16
	v_fmaak_f32 v113, v16, v22, 0x3f2aaada
	v_ldexp_f32 v23, v17, 1
	v_pk_mul_f32 v[16:17], v[4:5], v[112:113]
	v_ldexp_f32 v15, v14, 1
	v_fma_f32 v14, v4, s5, -v16
	v_fmac_f32_e32 v14, 0xb102e308, v4
	v_pk_add_f32 v[4:5], v[16:17], v[14:15]
	v_mov_b32_e32 v22, v16
	v_sub_f32_e32 v26, v5, v15
	v_pk_add_f32 v[24:25], v[4:5], v[16:17] neg_lo:[0,1] neg_hi:[0,1]
	v_sub_f32_e32 v16, v17, v26
	v_add_f32_e32 v23, v23, v16
	v_pk_add_f32 v[16:17], v[4:5], v[22:23]
	v_mov_b32_e32 v15, v4
	v_mov_b32_e32 v25, v17
	v_pk_add_f32 v[28:29], v[14:15], v[24:25] neg_lo:[0,1] neg_hi:[0,1]
	v_pk_add_f32 v[14:15], v[14:15], v[24:25]
	v_mov_b32_e32 v27, v4
	v_pk_add_f32 v[24:25], v[14:15], v[4:5] op_sel:[1,0] op_sel_hi:[0,1] neg_lo:[0,1] neg_hi:[0,1]
	v_mov_b32_e32 v26, v23
	v_mov_b32_e32 v22, v17
	v_mov_b32_e32 v23, v15
	v_pk_mov_b32 v[4:5], v[4:5], v[24:25] op_sel:[1,0]
	v_pk_add_f32 v[16:17], v[16:17], v[24:25] op_sel_hi:[1,0] neg_lo:[0,1] neg_hi:[0,1]
	v_pk_add_f32 v[4:5], v[22:23], v[4:5] neg_lo:[0,1] neg_hi:[0,1]
	v_mov_b32_e32 v16, v28
	v_pk_add_f32 v[4:5], v[26:27], v[4:5] neg_lo:[0,1] neg_hi:[0,1]
	v_mov_b32_e32 v29, v15
	v_pk_add_f32 v[16:17], v[16:17], v[4:5]
	s_nop 0
	v_pk_add_f32 v[22:23], v[16:17], v[16:17] op_sel:[0,1] op_sel_hi:[1,0]
	s_nop 0
	v_pk_add_f32 v[14:15], v[14:15], v[22:23] op_sel:[1,0] op_sel_hi:[0,1]
	v_mov_b32_e32 v17, v14
	v_mov_b32_e32 v5, v22
	v_pk_add_f32 v[22:23], v[16:17], v[28:29] neg_lo:[0,1] neg_hi:[0,1]
	s_nop 0
	v_sub_f32_e32 v15, v16, v22
	v_pk_add_f32 v[4:5], v[4:5], v[22:23] neg_lo:[0,1] neg_hi:[0,1]
	v_sub_f32_e32 v15, v28, v15
	v_add_f32_e32 v4, v4, v15
	v_add_f32_e32 v4, v4, v5
	v_add_f32_e32 v4, v14, v4
	v_cndmask_b32_e32 v4, v185, v4, vcc
	v_cmp_ngt_f32_e32 vcc, -1.0, v21
	v_mov_b64_e32 v[16:17], v[8:9]
	v_mov_b64_e32 v[14:15], v[6:7]
	v_cndmask_b32_e32 v4, v186, v4, vcc
	v_cmp_neq_f32_e32 vcc, -1.0, v21
	s_nop 1
	v_cndmask_b32_e32 v4, v187, v4, vcc
	v_cmp_lt_f32_e64 vcc, |v21|, s2
	s_nop 1
	v_cndmask_b32_e32 v4, v4, v21, vcc
	v_add_f32_e32 v2, v2, v4
	v_mul_f32_e32 v21, 0xc1000000, v2
	ds_write_b128 v30, v[18:21] offset:16
	s_and_saveexec_b64 s[2:3], s[0:1]
	s_cbranch_execz .LBB0_217
	v_add3_u32 v2, s20, -3, v195
	v_mov_b64_e32 v[4:5], s[88:89]
	v_mad_i64_i32 v[4:5], s[0:1], v2, s92, v[4:5]
	v_lshl_add_u64 v[4:5], v[104:105], 1, v[4:5]
	global_load_dwordx4 v[14:17], v[4:5], off
	global_load_dwordx4 v[10:13], v[4:5], off offset:64

.LBB0_221:
	s_or_b64 exec, exec, s[0:1]
	v_ashrrev_i32_e32 v4, 6, v42
	v_ashrrev_i32_e32 v5, 31, v4
	v_readlane_b32 s0, v244, 48
	v_and_b32_e32 v2, 63, v42
	v_lshlrev_b64 v[30:31], 13, v[4:5]
	v_readlane_b32 s1, v244, 49
	v_lshlrev_b32_e32 v2, 4, v2
	v_and_b32_e32 v5, 7, v42
	v_lshl_add_u64 v[30:31], s[0:1], 0, v[30:31]
	s_mov_b64 s[0:1], 0x10000
	v_lshl_add_u64 v[32:33], v[30:31], 0, s[0:1]
	v_lshl_add_u64 v[34:35], v[30:31], 0, v[2:3]
	v_lshl_add_u64 v[36:37], v[32:33], 0, v[2:3]
	v_or_b32_e32 v34, 0x1000, v2
	v_mov_b32_e32 v35, v3
	v_lshl_add_u64 v[36:37], v[30:31], 0, v[34:35]
	v_lshl_add_u64 v[34:35], v[32:33], 0, v[34:35]
	v_or_b32_e32 v34, 0x1400, v2
	v_mov_b32_e32 v35, v3
	v_lshl_add_u64 v[36:37], v[30:31], 0, v[34:35]
	v_lshl_add_u64 v[34:35], v[32:33], 0, v[34:35]
	v_or_b32_e32 v34, 0x1800, v2
	v_mov_b32_e32 v35, v3
	v_lshl_add_u64 v[36:37], v[30:31], 0, v[34:35]
	v_lshl_add_u64 v[34:35], v[32:33], 0, v[34:35]
	v_or_b32_e32 v34, 0x1c00, v2
	v_mov_b32_e32 v35, v3
	v_lshl_add_u64 v[30:31], v[30:31], 0, v[34:35]
	v_lshl_add_u64 v[32:33], v[32:33], 0, v[34:35]
	v_mov_b64_e32 v[30:31], s[88:89]
	v_lshrrev_b32_e32 v32, 4, v42
	v_bfe_u32 v33, v42, 4, 1
	v_mad_i64_i32 v[30:31], s[0:1], v113, s92, v[30:31]
	v_bitop3_b32 v34, v32, v5, 1 bitop3:0x6c
	v_bitop3_b32 v35, v33, v5, 2 bitop3:0x36
	v_bitop3_b32 v36, v33, v5, 4 bitop3:0x36
	v_bitop3_b32 v5, v33, v5, 6 bitop3:0x36
	v_lshl_add_u64 v[32:33], v[104:105], 1, v[30:31]
	v_lshl_add_u64 v[30:31], v[106:107], 1, v[30:31]
	v_lshlrev_b32_e32 v109, 4, v34
	v_lshlrev_b32_e32 v111, 4, v35
	v_lshlrev_b32_e32 v115, 4, v36
	global_load_dwordx4 v[34:37], v[32:33], off
	s_nop 0
	global_load_dwordx4 v[30:33], v[30:31], off
	s_movk_i32 s2, 0x780
	s_movk_i32 s3, 0xb80
	s_movk_i32 s4, 0xf80
	s_movk_i32 s5, 0x1380
	v_lshl_add_u32 v4, v4, 14, 0
	v_and_b32_e32 v108, 0x380, v2
	s_movk_i32 s6, 0x1780
	v_bitop3_b32 v110, v2, s2, v188 bitop3:0xc8
	v_bitop3_b32 v114, v2, s3, v189 bitop3:0xc8
	v_bitop3_b32 v116, v2, s4, v190 bitop3:0xc8
	v_lshlrev_b32_e32 v5, 4, v5
	v_bitop3_b32 v117, v2, s5, v191 bitop3:0xc8
	v_add3_u32 v108, v4, v108, v109
	v_add3_u32 v110, v4, v110, v111
	v_add3_u32 v114, v4, v114, v115
	v_add3_u32 v116, v4, v116, v5
	v_add3_u32 v109, v4, v117, v109
	s_movk_i32 s0, 0x1b80
	s_mov_b32 s2, 0xbfb8aa3b
	s_waitcnt vmcnt(18)
	ds_write_b128 v108, v[156:159] offset:16384
	ds_write_b128 v110, v[160:163] offset:16384
	ds_write_b128 v114, v[164:167] offset:16384
	ds_write_b128 v116, v[172:175] offset:16384
	ds_write_b128 v109, v[212:215] offset:16384
	ds_write_b128 v108, v[196:199] offset:24576
	ds_write_b128 v110, v[200:203] offset:24576
	ds_write_b128 v114, v[204:207] offset:24576
	ds_write_b128 v116, v[208:211] offset:24576
	ds_write_b128 v109, v[216:219] offset:24576
	v_bitop3_b32 v38, v2, s6, v192 bitop3:0xc8
	v_add3_u32 v38, v4, v38, v111
	ds_write_b128 v38, v[220:223] offset:16384
	ds_write_b128 v38, v[224:227] offset:24576
	v_bitop3_b32 v38, v2, s0, v193 bitop3:0xc8
	s_movk_i32 s0, 0x1f80
	v_bitop3_b32 v2, v2, s0, v194 bitop3:0xc8
	v_add3_u32 v38, v4, v38, v115
	v_add3_u32 v2, v4, v2, v5
	v_lshlrev_b32_e32 v5, 5, v104
	ds_write_b128 v38, v[228:231] offset:16384
	ds_write_b128 v38, v[232:235] offset:24576
	ds_write_b128 v2, v[236:239] offset:16384
	ds_write_b128 v2, v[248:251] offset:24576
	v_add_u32_e32 v2, 0, v5
	v_or_b32_e32 v38, 32, v5
	v_mov_b32_e32 v239, 0
	v_mov_b32_e32 v179, 1.0
	v_mov_b32_e32 v236, 1.0
	v_mov_b32_e32 v237, 1.0
	v_mov_b32_e32 v238, 1.0
	v_mov_b32_e32 v228, 1.0
	v_mov_b32_e32 v229, 1.0
	v_mov_b32_e32 v230, 1.0
	v_mov_b32_e32 v231, 1.0
	v_mov_b32_e32 v220, 1.0
	v_mov_b32_e32 v221, 1.0
	v_mov_b32_e32 v222, 1.0
	v_mov_b32_e32 v223, 1.0
	v_mov_b32_e32 v171, 1.0
	v_mov_b32_e32 v213, 1.0
	v_mov_b32_e32 v214, 1.0
	v_mov_b32_e32 v215, 1.0
	v_mov_b32_e32 v240, 0
	v_mov_b32_e32 v241, 0
	s_waitcnt lgkmcnt(0)
	s_barrier
	v_add_u32_e32 v196, 0, v38
	ds_read2_b32 v[38:39], v2 offset0:5 offset1:6
	ds_read2_b32 v[40:41], v196 offset0:5 offset1:6
	ds_read_b32 v44, v2 offset:28
	ds_read_b32 v45, v196 offset:28
	s_mov_b32 s0, 0x3fb8aa3b
	s_waitcnt lgkmcnt(3)
	v_mov_b32_e32 v46, v38
	v_or_b32_e32 v38, 64, v5
	s_waitcnt lgkmcnt(2)
	v_mov_b32_e32 v47, v40
	v_mov_b32_e32 v40, v39
	v_add_u32_e32 v197, 0, v38
	v_or_b32_e32 v38, 0x60, v5
	v_pk_mul_f32 v[110:111], v[40:41], s[2:3] op_sel_hi:[1,0]
	v_add_u32_e32 v198, 0, v38
	ds_read2_b32 v[38:39], v197 offset0:5 offset1:6
	ds_read2_b32 v[40:41], v198 offset0:5 offset1:6
	v_pk_mul_f32 v[108:109], v[46:47], s[2:3] op_sel_hi:[1,0]
	s_waitcnt lgkmcnt(2)
	v_pk_mul_f32 v[114:115], v[44:45], s[0:1] op_sel_hi:[1,0]
	ds_read_b32 v44, v197 offset:28
	ds_read_b32 v45, v198 offset:28
	s_waitcnt lgkmcnt(3)
	v_mov_b32_e32 v46, v38
	v_or_b32_e32 v38, 0x80, v5
	s_waitcnt lgkmcnt(2)
	v_mov_b32_e32 v47, v40
	v_mov_b32_e32 v40, v39
	v_add_u32_e32 v199, 0, v38
	v_or_b32_e32 v38, 0xa0, v5
	v_pk_mul_f32 v[118:119], v[40:41], s[2:3] op_sel_hi:[1,0]
	v_add_u32_e32 v200, 0, v38
	ds_read2_b32 v[38:39], v199 offset0:5 offset1:6
	ds_read2_b32 v[40:41], v200 offset0:5 offset1:6
	v_pk_mul_f32 v[116:117], v[46:47], s[2:3] op_sel_hi:[1,0]
	s_waitcnt lgkmcnt(2)
	v_pk_mul_f32 v[120:121], v[44:45], s[0:1] op_sel_hi:[1,0]
	ds_read_b32 v44, v199 offset:28
	ds_read_b32 v45, v200 offset:28
	s_waitcnt lgkmcnt(3)
	v_mov_b32_e32 v46, v38
	v_or_b32_e32 v38, 0xc0, v5
	s_waitcnt lgkmcnt(2)
	v_mov_b32_e32 v47, v40
	v_mov_b32_e32 v40, v39
	v_add_u32_e32 v201, 0, v38
	v_or_b32_e32 v38, 0xe0, v5
	v_pk_mul_f32 v[124:125], v[40:41], s[2:3] op_sel_hi:[1,0]
	v_add_u32_e32 v202, 0, v38
	ds_read2_b32 v[38:39], v201 offset0:5 offset1:6
	ds_read2_b32 v[40:41], v202 offset0:5 offset1:6
	v_pk_mul_f32 v[122:123], v[46:47], s[2:3] op_sel_hi:[1,0]
	s_waitcnt lgkmcnt(2)
	v_pk_mul_f32 v[126:127], v[44:45], s[0:1] op_sel_hi:[1,0]
	ds_read_b32 v44, v201 offset:28
	ds_read_b32 v45, v202 offset:28
	s_waitcnt lgkmcnt(3)
	v_mov_b32_e32 v46, v38
	v_lshlrev_b32_e32 v38, 5, v106
	s_waitcnt lgkmcnt(2)
	v_mov_b32_e32 v47, v40
	v_mov_b32_e32 v40, v39
	v_add_u32_e32 v203, 0, v38
	v_or_b32_e32 v38, 0x420, v5
	v_pk_mul_f32 v[130:131], v[40:41], s[2:3] op_sel_hi:[1,0]
	v_add_u32_e32 v204, 0, v38
	ds_read2_b32 v[38:39], v203 offset0:5 offset1:6
	ds_read2_b32 v[40:41], v204 offset0:5 offset1:6
	v_pk_mul_f32 v[128:129], v[46:47], s[2:3] op_sel_hi:[1,0]
	s_waitcnt lgkmcnt(2)
	v_pk_mul_f32 v[132:133], v[44:45], s[0:1] op_sel_hi:[1,0]
	ds_read_b32 v44, v203 offset:28
	ds_read_b32 v45, v204 offset:28
	s_waitcnt lgkmcnt(3)
	v_mov_b32_e32 v46, v38
	v_or_b32_e32 v38, 0x440, v5
	s_waitcnt lgkmcnt(2)
	v_mov_b32_e32 v47, v40
	v_mov_b32_e32 v40, v39
	v_add_u32_e32 v205, 0, v38
	v_or_b32_e32 v38, 0x460, v5
	v_pk_mul_f32 v[136:137], v[40:41], s[2:3] op_sel_hi:[1,0]
	v_add_u32_e32 v206, 0, v38
	ds_read2_b32 v[38:39], v205 offset0:5 offset1:6
	ds_read2_b32 v[40:41], v206 offset0:5 offset1:6
	v_pk_mul_f32 v[134:135], v[46:47], s[2:3] op_sel_hi:[1,0]
	s_waitcnt lgkmcnt(2)
	v_pk_mul_f32 v[138:139], v[44:45], s[0:1] op_sel_hi:[1,0]
	ds_read_b32 v44, v205 offset:28
	ds_read_b32 v45, v206 offset:28
	s_waitcnt lgkmcnt(3)
	v_mov_b32_e32 v46, v38
	v_or_b32_e32 v38, 0x480, v5
	s_waitcnt lgkmcnt(2)
	v_mov_b32_e32 v47, v40
	v_mov_b32_e32 v40, v39
	v_add_u32_e32 v207, 0, v38
	v_or_b32_e32 v38, 0x4a0, v5
	v_pk_mul_f32 v[142:143], v[40:41], s[2:3] op_sel_hi:[1,0]
	v_add_u32_e32 v208, 0, v38
	ds_read2_b32 v[38:39], v207 offset0:5 offset1:6
	ds_read2_b32 v[40:41], v208 offset0:5 offset1:6
	v_pk_mul_f32 v[140:141], v[46:47], s[2:3] op_sel_hi:[1,0]
	s_waitcnt lgkmcnt(2)
	v_pk_mul_f32 v[144:145], v[44:45], s[0:1] op_sel_hi:[1,0]
	ds_read_b32 v44, v207 offset:28
	ds_read_b32 v45, v208 offset:28
	s_waitcnt lgkmcnt(3)
	v_mov_b32_e32 v46, v38
	v_or_b32_e32 v38, 0x4c0, v5
	s_waitcnt lgkmcnt(2)
	v_mov_b32_e32 v47, v40
	v_mov_b32_e32 v40, v39
	v_add_u32_e32 v209, 0, v38
	v_or_b32_e32 v5, 0x4e0, v5
	v_pk_mul_f32 v[148:149], v[40:41], s[2:3] op_sel_hi:[1,0]
	v_add_u32_e32 v210, 0, v5
	ds_read2_b32 v[38:39], v209 offset0:5 offset1:6
	ds_read2_b32 v[40:41], v210 offset0:5 offset1:6
	s_waitcnt lgkmcnt(2)
	v_pk_mul_f32 v[150:151], v[44:45], s[0:1] op_sel_hi:[1,0]
	ds_read_b32 v44, v209 offset:28
	ds_read_b32 v45, v210 offset:28
	v_pk_mul_f32 v[146:147], v[46:47], s[2:3] op_sel_hi:[1,0]
	s_waitcnt lgkmcnt(3)
	v_mov_b32_e32 v46, v38
	v_lshlrev_b32_e32 v5, 1, v195
	v_and_b32_e32 v38, 3, v42
	s_waitcnt lgkmcnt(2)
	v_mov_b32_e32 v47, v40
	v_mov_b32_e32 v40, v39
	v_and_or_b32 v5, v5, 24, v38
	v_lshrrev_b32_e32 v38, 1, v42
	v_bfe_u32 v39, v42, 1, 3
	v_bitop3_b32 v38, v43, v38, 7 bitop3:0x78
	v_lshl_add_u32 v4, v5, 7, v4
	v_bitop3_b32 v5, v43, v39, 4 bitop3:0x36
	v_lshlrev_b32_e32 v38, 4, v38
	v_lshlrev_b32_e32 v5, 4, v5
	v_pk_mul_f32 v[152:153], v[46:47], s[2:3] op_sel_hi:[1,0]
	v_pk_mul_f32 v[154:155], v[40:41], s[2:3] op_sel_hi:[1,0]
	s_waitcnt lgkmcnt(0)
	v_pk_mul_f32 v[156:157], v[44:45], s[0:1] op_sel_hi:[1,0]
	s_mov_b32 s2, 0
	v_add_u32_e32 v211, v4, v38
	v_add_u32_e32 v212, v4, v5
	v_mov_b32_e32 v242, 0
	v_mov_b32_e32 v232, 0
	v_mov_b32_e32 v233, 0
	v_mov_b32_e32 v234, 0
	v_mov_b32_e32 v235, 0
	v_mov_b32_e32 v224, 0
	v_mov_b32_e32 v225, 0
	v_mov_b32_e32 v226, 0
	v_mov_b32_e32 v227, 0
	v_mov_b32_e32 v216, 0
	v_mov_b32_e32 v217, 0
	v_mov_b32_e32 v218, 0
	v_mov_b32_e32 v219, 0
	s_waitcnt vmcnt(0)
	s_branch .LBB0_223
